# SOFTMAX epilogue: part-1 exponentials kept in the accumulator registers, part 2 multiplies by exp(mx_wave-M)/L instead of recomputing exp(x-M) (f32, one exp per element instead of two)
# baseline (speedup 1.0000x reference)
.LBB0_453:
	s_or_b64 exec, exec, s[4:5]
	v_add_u32_e32 v10, 0, v168
	s_waitcnt lgkmcnt(0)
	s_barrier
	v_add_u32_e32 v14, 0x20000, v10
	s_waitcnt lgkmcnt(0)
	ds_read_b128 v[10:13], v14 offset:16
	ds_read_b128 v[160:163], v14
	v_readlane_b32 s6, v253, 40
	v_readlane_b32 s7, v253, 41
	s_mov_b32 s17, s29
	s_waitcnt lgkmcnt(0)
	v_max_f32_e32 v15, v12, v12
	v_max_f32_e32 v16, v10, v10
	v_max_f32_e32 v15, v16, v15
	v_max3_f32 v15, v160, v162, v15
	v_sub_f32_e32 v17, v162, v15
	v_sub_f32_e32 v12, v12, v15
	v_sub_f32_e32 v16, v160, v15
	v_mul_f32_e32 v17, 0x3fb8aa3b, v17
	v_sub_f32_e32 v10, v10, v15
	v_mul_f32_e32 v12, 0x3fb8aa3b, v12
	v_mul_f32_e32 v16, 0x3fb8aa3b, v16
	v_exp_f32_e32 v156, v17
	v_mul_f32_e32 v10, 0x3fb8aa3b, v10
	v_exp_f32_e32 v157, v12
	v_exp_f32_e32 v16, v16
	v_exp_f32_e32 v17, v10
	v_mov_b32_e32 v12, v163
	v_mov_b32_e32 v10, v161
	v_pk_mul_f32 v[12:13], v[12:13], v[156:157]
	v_pk_fma_f32 v[10:11], v[10:11], v[16:17], v[12:13]
	v_add_f32_e32 v12, v10, v11
	v_div_scale_f32 v13, s[4:5], v12, v12, 1.0
	v_rcp_f32_e32 v16, v13
	v_lshl_or_b32 v10, s35, 8, v167
	v_ashrrev_i32_e32 v11, 31, v10
	v_fma_f32 v17, -v13, v16, 1.0
	v_fmac_f32_e32 v16, v17, v16
	v_div_scale_f32 v17, vcc, 1.0, v12, 1.0
	v_mul_f32_e32 v156, v17, v16
	v_fma_f32 v157, -v13, v156, v17
	v_fmac_f32_e32 v156, v157, v16
	v_fma_f32 v13, -v13, v156, v17
	v_div_fmas_f32 v13, v13, v16, v156
	v_div_fixup_f32 v156, v13, v12, 1.0
	v_sub_f32_e32 v186, v178, v15
	v_mul_f32_e32 v186, 0x3fb8aa3b, v186
	v_exp_f32_e32 v186, v186
	s_nop 0
	v_mul_f32_e32 v156, v156, v186
	v_lshlrev_b64 v[12:13], 11, v[146:147]
	v_lshl_add_u64 v[16:17], s[6:7], 0, v[12:13]
	v_mov_b32_e32 v12, v126
	v_mov_b32_e32 v126, v12
	v_mov_b32_e32 v12, v127
	v_mov_b32_e32 v127, v12
	v_lshlrev_b64 v[12:13], 1, v[10:11]
	v_lshl_add_u64 v[10:11], v[16:17], 0, v[12:13]
	v_mul_f32_e32 v16, v126, v156
	v_mul_f32_e32 v17, v127, v156
	v_cvt_pk_bf16_f32 v126, v16, v17
	v_mov_b32_e32 v17, v129
	v_mov_b32_e32 v16, v128
	v_mul_f32_e32 v17, v17, v156
	v_mul_f32_e32 v16, v16, v156
	v_cvt_pk_bf16_f32 v127, v16, v17
	v_mov_b32_e32 v17, v123
	v_mul_f32_e32 v16, v122, v156
	v_mov_b32_e32 v122, v124
	v_mov_b32_e32 v123, v125
	v_mul_f32_e32 v17, v17, v156
	v_cvt_pk_bf16_f32 v128, v16, v17
	v_mul_f32_e32 v16, v122, v156
	v_mul_f32_e32 v17, v123, v156
	v_cvt_pk_bf16_f32 v129, v16, v17
	v_mul_f32_e32 v16, v118, v156
	v_mul_f32_e32 v17, v119, v156
	global_store_dwordx4 v[10:11], v[126:129], off
	v_cvt_pk_bf16_f32 v118, v16, v17
	v_mov_b32_e32 v16, v120
	v_mov_b32_e32 v17, v121
	v_mul_f32_e32 v16, v16, v156
	v_mul_f32_e32 v17, v17, v156
	v_cvt_pk_bf16_f32 v119, v16, v17
	v_mul_f32_e32 v16, v114, v156
	v_mov_b32_e32 v17, v115
	v_mov_b32_e32 v114, v116
	v_mov_b32_e32 v15, v117
	s_mov_b32 s35, s90
	v_mul_f32_e32 v17, v17, v156
	v_cvt_pk_bf16_f32 v120, v16, v17
	v_mul_f32_e32 v16, v114, v156
	v_mul_f32_e32 v15, v15, v156
	v_cvt_pk_bf16_f32 v121, v16, v15
	ds_read_b128 v[114:117], v14 offset:528
	ds_read_b128 v[122:125], v14 offset:512
	global_store_dwordx4 v[10:11], v[118:121], off offset:256
	s_waitcnt lgkmcnt(0)
	v_max_f32_e32 v15, v116, v116
	v_max_f32_e32 v16, v114, v114
	v_max_f32_e32 v15, v16, v15
	v_max3_f32 v15, v122, v124, v15
	v_sub_f32_e32 v17, v124, v15
	v_mul_f32_e32 v17, 0x3fb8aa3b, v17
	v_exp_f32_e32 v126, v17
	v_sub_f32_e32 v17, v114, v15
	v_sub_f32_e32 v114, v116, v15
	v_sub_f32_e32 v16, v122, v15
	v_mul_f32_e32 v114, 0x3fb8aa3b, v114
	v_mul_f32_e32 v16, 0x3fb8aa3b, v16
	v_mul_f32_e32 v17, 0x3fb8aa3b, v17
	v_exp_f32_e32 v127, v114
	v_exp_f32_e32 v16, v16
	v_exp_f32_e32 v17, v17
	v_mov_b32_e32 v116, v125
	v_mov_b32_e32 v114, v123
	v_pk_mul_f32 v[116:117], v[116:117], v[126:127]
	v_pk_fma_f32 v[16:17], v[114:115], v[16:17], v[116:117]
	v_add_f32_e32 v16, v16, v17
	v_div_scale_f32 v17, s[4:5], v16, v16, 1.0
	v_rcp_f32_e32 v114, v17
	s_nop 0
	v_fma_f32 v115, -v17, v114, 1.0
	v_fmac_f32_e32 v114, v115, v114
	v_div_scale_f32 v115, vcc, 1.0, v16, 1.0
	v_mul_f32_e32 v116, v115, v114
	v_fma_f32 v117, -v17, v116, v115
	v_fmac_f32_e32 v116, v117, v114
	v_fma_f32 v17, -v17, v116, v115
	v_div_fmas_f32 v17, v17, v114, v116
	v_div_fixup_f32 v114, v17, v16, 1.0
	v_sub_f32_e32 v186, v179, v15
	v_mul_f32_e32 v186, 0x3fb8aa3b, v186
	v_exp_f32_e32 v186, v186
	s_nop 0
	v_mul_f32_e32 v114, v114, v186
	v_mul_f32_e32 v110, v110, v114
	v_mul_f32_e32 v111, v111, v114
	v_cvt_pk_bf16_f32 v110, v110, v111
	v_mov_b32_e32 v111, v112
	v_mov_b32_e32 v112, v113
	v_or_b32_e32 v16, 16, v146
	v_ashrrev_i32_e32 v17, 31, v16
	v_lshlrev_b64 v[16:17], 11, v[16:17]
	v_lshl_add_u64 v[16:17], s[6:7], 0, v[16:17]
	v_lshl_add_u64 v[16:17], v[16:17], 0, v[12:13]
	v_mul_f32_e32 v111, v111, v114
	v_mul_f32_e32 v112, v112, v114
	v_mul_f32_e32 v106, v106, v114
	v_mul_f32_e32 v107, v107, v114
	v_mul_f32_e32 v102, v102, v114
	v_mul_f32_e32 v103, v103, v114
	v_cvt_pk_bf16_f32 v111, v111, v112
	v_cvt_pk_bf16_f32 v112, v106, v107
	v_mul_f32_e32 v106, v108, v114
	v_mul_f32_e32 v107, v109, v114
	v_cvt_pk_bf16_f32 v113, v106, v107
	global_store_dwordx4 v[16:17], v[110:113], off
	v_cvt_pk_bf16_f32 v102, v102, v103
	v_mov_b32_e32 v103, v104
	v_mov_b32_e32 v104, v105
	v_mov_b32_e32 v15, v101
	v_mul_f32_e32 v103, v103, v114
	v_mul_f32_e32 v104, v104, v114
	v_mul_f32_e32 v98, v98, v114
	v_cvt_pk_bf16_f32 v103, v103, v104
	v_mul_f32_e32 v99, v99, v114
	v_cvt_pk_bf16_f32 v104, v98, v99
	v_mul_f32_e32 v98, v100, v114
	v_mul_f32_e32 v15, v15, v114
	v_cvt_pk_bf16_f32 v105, v98, v15
	ds_read_b128 v[98:101], v14 offset:1040
	ds_read_b128 v[106:109], v14 offset:1024
	global_store_dwordx4 v[16:17], v[102:105], off offset:256
	s_waitcnt lgkmcnt(0)
	v_max_f32_e32 v15, v100, v100
	v_max_f32_e32 v110, v98, v98
	v_max_f32_e32 v15, v110, v15
	v_max3_f32 v15, v106, v108, v15
	v_sub_f32_e32 v106, v106, v15
	v_mul_f32_e32 v106, 0x3fb8aa3b, v106
	v_exp_f32_e32 v110, v106
	v_sub_f32_e32 v106, v108, v15
	v_sub_f32_e32 v100, v100, v15
	v_mul_f32_e32 v106, 0x3fb8aa3b, v106
	v_sub_f32_e32 v98, v98, v15
	v_mul_f32_e32 v100, 0x3fb8aa3b, v100
	v_exp_f32_e32 v112, v106
	v_mul_f32_e32 v98, 0x3fb8aa3b, v98
	v_exp_f32_e32 v113, v100
	v_exp_f32_e32 v111, v98
	v_mov_b32_e32 v100, v109
	v_mov_b32_e32 v98, v107
	v_pk_mul_f32 v[100:101], v[100:101], v[112:113]
	v_pk_fma_f32 v[98:99], v[98:99], v[110:111], v[100:101]
	v_add_f32_e32 v98, v98, v99
	v_div_scale_f32 v99, s[4:5], v98, v98, 1.0
	v_rcp_f32_e32 v100, v99
	s_nop 0
	v_fma_f32 v16, -v99, v100, 1.0
	v_fmac_f32_e32 v100, v16, v100
	v_div_scale_f32 v16, vcc, 1.0, v98, 1.0
	v_mul_f32_e32 v17, v16, v100
	v_fma_f32 v101, -v99, v17, v16
	v_fmac_f32_e32 v17, v101, v100
	v_fma_f32 v16, -v99, v17, v16
	v_div_fmas_f32 v16, v16, v100, v17
	v_div_fixup_f32 v98, v16, v98, 1.0
	v_sub_f32_e32 v186, v180, v15
	v_mul_f32_e32 v186, 0x3fb8aa3b, v186
	v_exp_f32_e32 v186, v186
	s_nop 0
	v_mul_f32_e32 v98, v98, v186
	v_mul_f32_e32 v94, v94, v98
	v_mul_f32_e32 v95, v95, v98
	v_cvt_pk_bf16_f32 v94, v94, v95
	v_mov_b32_e32 v95, v96
	v_mov_b32_e32 v96, v97
	v_or_b32_e32 v16, 32, v146
	v_ashrrev_i32_e32 v17, 31, v16
	v_lshlrev_b64 v[16:17], 11, v[16:17]
	v_lshl_add_u64 v[16:17], s[6:7], 0, v[16:17]
	v_lshl_add_u64 v[16:17], v[16:17], 0, v[12:13]
	v_mul_f32_e32 v95, v95, v98
	v_mul_f32_e32 v96, v96, v98
	v_mul_f32_e32 v90, v90, v98
	v_mul_f32_e32 v91, v91, v98
	v_mul_f32_e32 v86, v86, v98
	v_mul_f32_e32 v87, v87, v98
	v_cvt_pk_bf16_f32 v95, v95, v96
	v_cvt_pk_bf16_f32 v96, v90, v91
	v_mul_f32_e32 v90, v92, v98
	v_mul_f32_e32 v91, v93, v98
	v_cvt_pk_bf16_f32 v97, v90, v91
	global_store_dwordx4 v[16:17], v[94:97], off
	v_cvt_pk_bf16_f32 v86, v86, v87
	v_mov_b32_e32 v87, v88
	v_mov_b32_e32 v88, v89
	v_mov_b32_e32 v15, v85
	v_mul_f32_e32 v87, v87, v98
	v_mul_f32_e32 v88, v88, v98
	v_mul_f32_e32 v82, v82, v98
	v_cvt_pk_bf16_f32 v87, v87, v88
	v_mul_f32_e32 v83, v83, v98
	v_cvt_pk_bf16_f32 v88, v82, v83
	v_mul_f32_e32 v82, v84, v98
	v_mul_f32_e32 v15, v15, v98
	v_cvt_pk_bf16_f32 v89, v82, v15
	ds_read_b128 v[82:85], v14 offset:1552
	ds_read_b128 v[90:93], v14 offset:1536
	global_store_dwordx4 v[16:17], v[86:89], off offset:256
	s_waitcnt lgkmcnt(0)
	v_max_f32_e32 v15, v84, v84
	v_max_f32_e32 v94, v82, v82
	v_max_f32_e32 v15, v94, v15
	v_max3_f32 v15, v90, v92, v15
	v_sub_f32_e32 v90, v90, v15
	v_mul_f32_e32 v90, 0x3fb8aa3b, v90
	v_exp_f32_e32 v94, v90
	v_sub_f32_e32 v90, v92, v15
	v_sub_f32_e32 v84, v84, v15
	v_mul_f32_e32 v90, 0x3fb8aa3b, v90
	v_sub_f32_e32 v82, v82, v15
	v_mul_f32_e32 v84, 0x3fb8aa3b, v84
	v_exp_f32_e32 v96, v90
	v_mul_f32_e32 v82, 0x3fb8aa3b, v82
	v_exp_f32_e32 v97, v84
	v_exp_f32_e32 v95, v82
	v_mov_b32_e32 v84, v93
	v_mov_b32_e32 v82, v91
	v_pk_mul_f32 v[84:85], v[84:85], v[96:97]
	v_pk_fma_f32 v[82:83], v[82:83], v[94:95], v[84:85]
	v_add_f32_e32 v82, v82, v83
	v_div_scale_f32 v83, s[4:5], v82, v82, 1.0
	v_rcp_f32_e32 v84, v83
	s_nop 0
	v_fma_f32 v16, -v83, v84, 1.0
	v_fmac_f32_e32 v84, v16, v84
	v_div_scale_f32 v16, vcc, 1.0, v82, 1.0
	v_mul_f32_e32 v17, v16, v84
	v_fma_f32 v85, -v83, v17, v16
	v_fmac_f32_e32 v17, v85, v84
	v_fma_f32 v16, -v83, v17, v16
	v_div_fmas_f32 v16, v16, v84, v17
	v_div_fixup_f32 v82, v16, v82, 1.0
	v_sub_f32_e32 v186, v181, v15
	v_mul_f32_e32 v186, 0x3fb8aa3b, v186
	v_exp_f32_e32 v186, v186
	s_nop 0
	v_mul_f32_e32 v82, v82, v186
	v_or_b32_e32 v16, 48, v146
	v_ashrrev_i32_e32 v17, 31, v16
	v_lshlrev_b64 v[16:17], 11, v[16:17]
	v_lshl_add_u64 v[16:17], s[6:7], 0, v[16:17]
	v_lshl_add_u64 v[12:13], v[16:17], 0, v[12:13]
	v_mul_f32_e32 v17, v79, v82
	v_mul_f32_e32 v16, v78, v82
	v_cvt_pk_bf16_f32 v78, v16, v17
	v_mov_b32_e32 v17, v81
	v_mov_b32_e32 v16, v80
	v_mul_f32_e32 v17, v17, v82
	v_mul_f32_e32 v16, v16, v82
	v_cvt_pk_bf16_f32 v79, v16, v17
	v_mov_b32_e32 v17, v75
	v_mul_f32_e32 v16, v74, v82
	v_mov_b32_e32 v74, v76
	v_mov_b32_e32 v75, v77
	v_mul_f32_e32 v17, v17, v82
	v_cvt_pk_bf16_f32 v80, v16, v17
	v_mul_f32_e32 v16, v74, v82
	v_mul_f32_e32 v17, v75, v82
	v_cvt_pk_bf16_f32 v81, v16, v17
	v_mul_f32_e32 v16, v70, v82
	v_mul_f32_e32 v17, v71, v82
	global_store_dwordx4 v[12:13], v[78:81], off
	v_cvt_pk_bf16_f32 v70, v16, v17
	v_mov_b32_e32 v16, v72
	v_mov_b32_e32 v17, v73
	v_mul_f32_e32 v16, v16, v82
	v_mul_f32_e32 v17, v17, v82
	v_cvt_pk_bf16_f32 v71, v16, v17
	v_mul_f32_e32 v16, v66, v82
	v_mov_b32_e32 v17, v67
	v_mov_b32_e32 v66, v68
	v_mov_b32_e32 v15, v69
	v_mul_f32_e32 v17, v17, v82
	v_cvt_pk_bf16_f32 v72, v16, v17
	v_mul_f32_e32 v16, v66, v82
	v_mul_f32_e32 v15, v15, v82
	v_cvt_pk_bf16_f32 v73, v16, v15
	ds_read_b128 v[66:69], v14 offset:4112
	ds_read_b128 v[74:77], v14 offset:4096
	global_store_dwordx4 v[12:13], v[70:73], off offset:256
	s_waitcnt lgkmcnt(0)
	v_max_f32_e32 v15, v68, v68
	v_max_f32_e32 v16, v66, v66
	v_max_f32_e32 v15, v16, v15
	v_max3_f32 v15, v74, v76, v15
	v_sub_f32_e32 v17, v76, v15
	v_mul_f32_e32 v17, 0x3fb8aa3b, v17
	v_exp_f32_e32 v78, v17
	v_sub_f32_e32 v17, v66, v15
	v_sub_f32_e32 v66, v68, v15
	v_sub_f32_e32 v16, v74, v15
	v_mul_f32_e32 v66, 0x3fb8aa3b, v66
	v_mul_f32_e32 v16, 0x3fb8aa3b, v16
	v_mul_f32_e32 v17, 0x3fb8aa3b, v17
	v_exp_f32_e32 v79, v66
	v_exp_f32_e32 v16, v16
	v_exp_f32_e32 v17, v17
	v_mov_b32_e32 v68, v77
	v_mov_b32_e32 v66, v75
	v_pk_mul_f32 v[68:69], v[68:69], v[78:79]
	s_nop 0
	v_pk_fma_f32 v[16:17], v[66:67], v[16:17], v[68:69]
	v_mov_b32_e32 v68, v149
	v_add_f32_e32 v16, v16, v17
	v_div_scale_f32 v17, s[4:5], v16, v16, 1.0
	v_rcp_f32_e32 v66, v17
	v_mov_b32_e32 v69, v68
	s_mov_b32 s4, 0x40000
	v_fma_f32 v12, -v17, v66, 1.0
	v_fmac_f32_e32 v66, v12, v66
	v_div_scale_f32 v12, vcc, 1.0, v16, 1.0
	v_mul_f32_e32 v13, v12, v66
	v_fma_f32 v67, -v17, v13, v12
	v_fmac_f32_e32 v13, v67, v66
	v_fma_f32 v12, -v17, v13, v12
	v_mov_b32_e32 v17, v154
	v_mov_b32_e32 v67, v155
	v_div_fmas_f32 v12, v12, v66, v13
	v_div_fixup_f32 v16, v12, v16, 1.0
	v_sub_f32_e32 v186, v182, v15
	v_mul_f32_e32 v186, 0x3fb8aa3b, v186
	v_exp_f32_e32 v186, v186
	s_nop 0
	v_mul_f32_e32 v16, v16, v186
	v_mul_f32_e32 v12, v17, v16
	v_mul_f32_e32 v13, v67, v16
	v_cvt_pk_bf16_f32 v66, v12, v13
	v_mov_b32_e32 v12, v152
	v_mov_b32_e32 v13, v153
	v_mov_b32_e32 v17, v150
	v_mul_f32_e32 v12, v12, v16
	v_mul_f32_e32 v13, v13, v16
	v_cvt_pk_bf16_f32 v67, v12, v13
	v_mul_f32_e32 v12, v17, v16
	v_mov_b32_e32 v13, v151
	v_mov_b32_e32 v17, v148
	v_mul_f32_e32 v13, v13, v16
	v_cvt_pk_bf16_f32 v68, v12, v13
	v_mul_f32_e32 v12, v17, v16
	v_mul_f32_e32 v13, v69, v16
	v_cvt_pk_bf16_f32 v69, v12, v13
	v_mov_b32_e32 v12, v62
	v_mov_b32_e32 v17, v12
	v_mov_b32_e32 v12, v63
	v_mov_b32_e32 v62, v12
	v_add_co_u32_e32 v12, vcc, s4, v10
	s_nop 1
	v_addc_co_u32_e32 v13, vcc, 0, v11, vcc
	global_store_dwordx4 v[12:13], v[66:69], off
	v_mul_f32_e32 v13, v62, v16
	v_mul_f32_e32 v12, v17, v16
	v_cvt_pk_bf16_f32 v66, v12, v13
	v_mov_b32_e32 v13, v55
	v_mov_b32_e32 v12, v54
	v_mov_b32_e32 v17, v52
	v_mul_f32_e32 v13, v13, v16
	v_mul_f32_e32 v12, v12, v16
	v_cvt_pk_bf16_f32 v67, v12, v13
	v_mov_b32_e32 v13, v53
	v_mul_f32_e32 v12, v17, v16
	v_mov_b32_e32 v17, v50
	v_mov_b32_e32 v15, v51
	v_mul_f32_e32 v13, v13, v16
	v_cvt_pk_bf16_f32 v68, v12, v13
	v_mul_f32_e32 v12, v17, v16
	v_mul_f32_e32 v13, v15, v16
	v_cvt_pk_bf16_f32 v69, v12, v13
	ds_read_b128 v[50:53], v14 offset:4624
	ds_read_b128 v[70:73], v14 offset:4608
	s_waitcnt lgkmcnt(0)
	v_max_f32_e32 v12, v52, v52
	v_max_f32_e32 v13, v50, v50
	v_max_f32_e32 v12, v13, v12
	v_max3_f32 v15, v70, v72, v12
	v_sub_f32_e32 v13, v72, v15
	v_mul_f32_e32 v13, 0x3fb8aa3b, v13
	v_sub_f32_e32 v17, v52, v15
	v_sub_f32_e32 v12, v70, v15
	v_exp_f32_e32 v16, v13
	v_sub_f32_e32 v13, v50, v15
	v_mul_f32_e32 v17, 0x3fb8aa3b, v17
	v_mul_f32_e32 v12, 0x3fb8aa3b, v12
	v_mul_f32_e32 v13, 0x3fb8aa3b, v13
	v_exp_f32_e32 v17, v17
	v_exp_f32_e32 v12, v12
	v_exp_f32_e32 v13, v13
	v_mov_b32_e32 v52, v73
	v_mov_b32_e32 v50, v71
	v_pk_mul_f32 v[16:17], v[52:53], v[16:17]
	v_mov_b32_e32 v52, v57
	v_pk_fma_f32 v[12:13], v[50:51], v[12:13], v[16:17]
	v_add_f32_e32 v16, v12, v13
	v_div_scale_f32 v17, s[4:5], v16, v16, 1.0
	v_rcp_f32_e32 v50, v17
	s_mov_b64 s[4:5], 0x40000
	v_lshl_add_u64 v[12:13], v[10:11], 0, s[4:5]
	global_store_dwordx4 v[12:13], v[66:69], off offset:256
	v_fma_f32 v12, -v17, v50, 1.0
	v_fmac_f32_e32 v50, v12, v50
	v_div_scale_f32 v12, vcc, 1.0, v16, 1.0
	v_mul_f32_e32 v13, v12, v50
	v_fma_f32 v51, -v17, v13, v12
	v_fmac_f32_e32 v13, v51, v50
	v_fma_f32 v12, -v17, v13, v12
	v_mov_b32_e32 v17, v64
	v_mov_b32_e32 v51, v65
	v_div_fmas_f32 v12, v12, v50, v13
	v_div_fixup_f32 v16, v12, v16, 1.0
	v_sub_f32_e32 v186, v183, v15
	v_mul_f32_e32 v186, 0x3fb8aa3b, v186
	v_exp_f32_e32 v186, v186
	s_nop 0
	v_mul_f32_e32 v16, v16, v186
	v_mul_f32_e32 v12, v17, v16
	v_mul_f32_e32 v13, v51, v16
	v_cvt_pk_bf16_f32 v50, v12, v13
	v_mov_b32_e32 v12, v58
	v_mov_b32_e32 v13, v59
	v_mov_b32_e32 v17, v60
	v_mul_f32_e32 v12, v12, v16
	v_mul_f32_e32 v13, v13, v16
	v_cvt_pk_bf16_f32 v51, v12, v13
	v_mul_f32_e32 v12, v17, v16
	v_mov_b32_e32 v13, v61
	v_mov_b32_e32 v17, v56
	v_mov_b32_e32 v53, v52
	s_mov_b32 s4, 0x48000
	v_mul_f32_e32 v13, v13, v16
	v_cvt_pk_bf16_f32 v52, v12, v13
	v_mul_f32_e32 v12, v17, v16
	v_mul_f32_e32 v13, v53, v16
	v_cvt_pk_bf16_f32 v53, v12, v13
	v_mov_b32_e32 v12, v40
	v_mov_b32_e32 v17, v12
	v_mov_b32_e32 v12, v41
	v_mov_b32_e32 v40, v12
	v_add_co_u32_e32 v12, vcc, s4, v10
	s_nop 1
	v_addc_co_u32_e32 v13, vcc, 0, v11, vcc
	global_store_dwordx4 v[12:13], v[50:53], off
	v_mul_f32_e32 v13, v40, v16
	v_mul_f32_e32 v12, v17, v16
	v_cvt_pk_bf16_f32 v50, v12, v13
	v_mov_b32_e32 v13, v39
	v_mov_b32_e32 v12, v38
	v_mov_b32_e32 v17, v36
	v_mul_f32_e32 v13, v13, v16
	v_mul_f32_e32 v12, v12, v16
	v_cvt_pk_bf16_f32 v51, v12, v13
	v_mov_b32_e32 v13, v37
	v_mul_f32_e32 v12, v17, v16
	v_mov_b32_e32 v17, v34
	v_mov_b32_e32 v15, v35
	v_mul_f32_e32 v13, v13, v16
	v_cvt_pk_bf16_f32 v52, v12, v13
	v_mul_f32_e32 v12, v17, v16
	v_mul_f32_e32 v13, v15, v16
	v_cvt_pk_bf16_f32 v53, v12, v13
	ds_read_b128 v[34:37], v14 offset:5136
	ds_read_b128 v[38:41], v14 offset:5120
	s_waitcnt lgkmcnt(0)
	v_max_f32_e32 v12, v36, v36
	v_max_f32_e32 v13, v34, v34
	v_max_f32_e32 v12, v13, v12
	v_max3_f32 v15, v38, v40, v12
	v_sub_f32_e32 v13, v40, v15
	v_mul_f32_e32 v13, 0x3fb8aa3b, v13
	v_sub_f32_e32 v17, v36, v15
	v_sub_f32_e32 v12, v38, v15
	v_exp_f32_e32 v16, v13
	v_sub_f32_e32 v13, v34, v15
	v_mul_f32_e32 v17, 0x3fb8aa3b, v17
	v_mul_f32_e32 v12, 0x3fb8aa3b, v12
	v_mul_f32_e32 v13, 0x3fb8aa3b, v13
	v_exp_f32_e32 v17, v17
	v_exp_f32_e32 v12, v12
	v_exp_f32_e32 v13, v13
	v_mov_b32_e32 v36, v41
	v_mov_b32_e32 v34, v39
	v_pk_mul_f32 v[16:17], v[36:37], v[16:17]
	v_pk_fma_f32 v[12:13], v[34:35], v[12:13], v[16:17]
	v_add_f32_e32 v16, v12, v13
	v_div_scale_f32 v17, s[4:5], v16, v16, 1.0
	v_rcp_f32_e32 v34, v17
	s_mov_b64 s[4:5], 0x48000
	v_lshl_add_u64 v[12:13], v[10:11], 0, s[4:5]
	global_store_dwordx4 v[12:13], v[50:53], off offset:256
	v_fma_f32 v12, -v17, v34, 1.0
	v_fmac_f32_e32 v34, v12, v34
	v_div_scale_f32 v12, vcc, 1.0, v16, 1.0
	v_mul_f32_e32 v13, v12, v34
	v_fma_f32 v35, -v17, v13, v12
	v_fmac_f32_e32 v13, v35, v34
	v_fma_f32 v12, -v17, v13, v12
	v_mov_b32_e32 v17, v48
	v_mov_b32_e32 v35, v49
	v_div_fmas_f32 v12, v12, v34, v13
	v_div_fixup_f32 v38, v12, v16, 1.0
	v_sub_f32_e32 v186, v184, v15
	v_mul_f32_e32 v186, 0x3fb8aa3b, v186
	v_exp_f32_e32 v186, v186
	s_nop 0
	v_mul_f32_e32 v38, v38, v186
	v_mul_f32_e32 v12, v17, v38
	v_mul_f32_e32 v13, v35, v38
	v_cvt_pk_bf16_f32 v34, v12, v13
	v_mov_b32_e32 v12, v46
	v_mov_b32_e32 v13, v47
	v_mov_b32_e32 v16, v44
	v_mul_f32_e32 v12, v12, v38
	v_mul_f32_e32 v13, v13, v38
	v_cvt_pk_bf16_f32 v35, v12, v13
	v_mul_f32_e32 v12, v16, v38
	v_mov_b32_e32 v13, v45
	v_mov_b32_e32 v16, v42
	v_mov_b32_e32 v17, v43
	v_mul_f32_e32 v13, v13, v38
	v_cvt_pk_bf16_f32 v36, v12, v13
	v_mul_f32_e32 v12, v16, v38
	v_mul_f32_e32 v13, v17, v38
	v_cvt_pk_bf16_f32 v37, v12, v13
	v_mov_b32_e32 v12, v30
	v_mov_b32_e32 v16, v12
	v_mov_b32_e32 v12, v31
	v_mov_b32_e32 v17, v12
	s_mov_b32 s4, 0x50000
	v_add_co_u32_e32 v12, vcc, s4, v10
	s_nop 1
	v_addc_co_u32_e32 v13, vcc, 0, v11, vcc
	global_store_dwordx4 v[12:13], v[34:37], off
	v_mul_f32_e32 v13, v17, v38
	v_mul_f32_e32 v12, v16, v38
	v_cvt_pk_bf16_f32 v16, v12, v13
	v_mov_b32_e32 v13, v23
	v_mov_b32_e32 v12, v22
	v_mov_b32_e32 v17, v20
	v_mov_b32_e32 v20, v17
	v_mul_f32_e32 v13, v13, v38
	v_mul_f32_e32 v12, v12, v38
	v_cvt_pk_bf16_f32 v17, v12, v13
	v_mov_b32_e32 v13, v21
	v_mov_b32_e32 v15, v19
	v_mul_f32_e32 v12, v20, v38
	v_mov_b32_e32 v20, v18
	v_mul_f32_e32 v13, v13, v38
	v_cvt_pk_bf16_f32 v18, v12, v13
	v_mul_f32_e32 v12, v20, v38
	v_mul_f32_e32 v13, v15, v38
	v_cvt_pk_bf16_f32 v19, v12, v13
	ds_read_b128 v[20:23], v14 offset:5648
	ds_read_b128 v[12:15], v14 offset:5632
	s_waitcnt lgkmcnt(0)
	v_max_f32_e32 v30, v22, v22
	v_max_f32_e32 v31, v20, v20
	v_max_f32_e32 v30, v31, v30
	v_max3_f32 v36, v12, v14, v30
	v_sub_f32_e32 v12, v12, v36
	v_mul_f32_e32 v12, 0x3fb8aa3b, v12
	v_exp_f32_e32 v30, v12
	v_sub_f32_e32 v12, v14, v36
	v_mul_f32_e32 v12, 0x3fb8aa3b, v12
	v_sub_f32_e32 v14, v22, v36
	v_exp_f32_e32 v34, v12
	v_sub_f32_e32 v12, v20, v36
	v_mul_f32_e32 v14, 0x3fb8aa3b, v14
	v_mul_f32_e32 v12, 0x3fb8aa3b, v12
	v_exp_f32_e32 v35, v14
	v_exp_f32_e32 v31, v12
	v_mov_b32_e32 v22, v15
	v_mov_b32_e32 v20, v13
	v_pk_mul_f32 v[12:13], v[22:23], v[34:35]
	v_pk_fma_f32 v[12:13], v[20:21], v[30:31], v[12:13]
	v_add_f32_e32 v14, v12, v13
	v_div_scale_f32 v15, s[4:5], v14, v14, 1.0
	v_rcp_f32_e32 v20, v15
	s_mov_b64 s[4:5], 0x50000
	v_lshl_add_u64 v[12:13], v[10:11], 0, s[4:5]
	global_store_dwordx4 v[12:13], v[16:19], off offset:256
	v_fma_f32 v12, -v15, v20, 1.0
	v_fmac_f32_e32 v20, v12, v20
	v_div_scale_f32 v12, vcc, 1.0, v14, 1.0
	v_mul_f32_e32 v13, v12, v20
	v_fma_f32 v16, -v15, v13, v12
	v_fmac_f32_e32 v13, v16, v20
	v_fma_f32 v12, -v15, v13, v12
	v_div_fmas_f32 v12, v12, v20, v13
	v_mov_b32_e32 v13, v32
	v_mov_b32_e32 v15, v33
	v_div_fixup_f32 v18, v12, v14, 1.0
	v_sub_f32_e32 v186, v185, v36
	v_mul_f32_e32 v186, 0x3fb8aa3b, v186
	v_exp_f32_e32 v186, v186
	s_nop 0
	v_mul_f32_e32 v18, v18, v186
	v_mov_b32_e32 v14, v27
	v_mul_f32_e32 v12, v13, v18
	v_mul_f32_e32 v13, v15, v18
	v_cvt_pk_bf16_f32 v12, v12, v13
	v_mov_b32_e32 v13, v26
	v_mov_b32_e32 v15, v28
	v_mul_f32_e32 v13, v13, v18
	v_mul_f32_e32 v14, v14, v18
	v_cvt_pk_bf16_f32 v13, v13, v14
	v_mul_f32_e32 v14, v15, v18
	v_mov_b32_e32 v15, v29
	v_mov_b32_e32 v19, v24
	v_mov_b32_e32 v20, v25
	v_mul_f32_e32 v15, v15, v18
	v_cvt_pk_bf16_f32 v14, v14, v15
	v_mul_f32_e32 v15, v19, v18
	v_mul_f32_e32 v19, v20, v18
	v_cvt_pk_bf16_f32 v15, v15, v19
	v_mov_b32_e32 v19, v8
	v_mov_b32_e32 v8, v9
	s_mov_b64 s[4:5], 0x58000
	v_mov_b32_e32 v20, v8
	v_lshl_add_u64 v[16:17], v[10:11], 0, s[4:5]
	s_mov_b32 s4, 0x58000
	v_add_co_u32_e32 v8, vcc, s4, v10
	v_mul_f32_e32 v2, v2, v18
	s_nop 0
	v_addc_co_u32_e32 v9, vcc, 0, v11, vcc
	global_store_dwordx4 v[8:9], v[12:15], off
	v_mul_f32_e32 v8, v19, v18
	v_mul_f32_e32 v9, v20, v18
	v_mul_f32_e32 v3, v3, v18
	v_cvt_pk_bf16_f32 v8, v8, v9
	v_mul_f32_e32 v6, v6, v18
	v_mul_f32_e32 v7, v7, v18
	v_cvt_pk_bf16_f32 v9, v6, v7
	v_mul_f32_e32 v4, v4, v18
	v_mul_f32_e32 v5, v5, v18
	v_cvt_pk_bf16_f32 v10, v4, v5
	v_cvt_pk_bf16_f32 v11, v2, v3
	s_andn2_b64 vcc, exec, s[40:41]
	s_mov_b64 s[4:5], s[0:1]
	v_mov_b64_e32 v[2:3], v[144:145]
	global_store_dwordx4 v[16:17], v[8:11], off offset:256
	s_cbranch_vccz .LBB0_499

.LBB0_461:
	s_add_i32 s17, s4, 2
	s_add_i32 s42, 0, 0x10000
	s_cmp_eq_u32 s28, s4
	v_lshl_add_u64 v[150:151], v[148:149], 0, s[84:85]
	s_cselect_b64 vcc, -1, 0
	v_add_u32_e32 v171, s42, v166
	v_cndmask_b32_e32 v165, v151, v145, vcc
	v_cndmask_b32_e32 v164, v150, v144, vcc
	ds_read_b128 v[150:153], v171
	ds_read_b128 v[154:157], v171 offset:1024
	ds_read_b128 v[160:163], v171 offset:2048
	ds_read_b128 v[172:175], v171 offset:3072
	s_cselect_b32 s4, s0, s6
	s_cselect_b32 s5, s1, s7
	v_lshl_add_u64 v[208:209], v[148:149], 0, v[140:141]
	s_add_i32 m0, s8, 0xc000
	ds_read_b128 v[176:179], v169
	ds_read_b128 v[180:183], v169 offset:1024
	ds_read_b128 v[184:187], v169 offset:2048
	ds_read_b128 v[188:191], v169 offset:3072
	ds_read_b128 v[192:195], v169 offset:4096
	ds_read_b128 v[196:199], v169 offset:5120
	ds_read_b128 v[200:203], v169 offset:6144
	ds_read_b128 v[204:207], v169 offset:7168
	global_load_lds_dwordx4 v[208:209], off
	v_lshl_add_u64 v[208:209], v[148:149], 0, v[142:143]
	s_add_i32 m0, s8, 0xe000
	s_nop 0
	global_load_lds_dwordx4 v[208:209], off
	s_waitcnt lgkmcnt(8)
	s_barrier
	s_waitcnt lgkmcnt(0)
	s_waitcnt lgkmcnt(0)
	v_mfma_f32_16x16x32_bf16 v[126:129], v[150:153], v[176:179], v[126:129]
	v_mfma_f32_16x16x32_bf16 v[122:125], v[160:163], v[176:179], v[122:125]
	v_mfma_f32_16x16x32_bf16 v[110:113], v[150:153], v[184:187], v[110:113]
	v_mfma_f32_16x16x32_bf16 v[106:109], v[160:163], v[184:187], v[106:109]
	v_mfma_f32_16x16x32_bf16 v[94:97], v[150:153], v[192:195], v[94:97]
	v_mfma_f32_16x16x32_bf16 v[90:93], v[160:163], v[192:195], v[90:93]
	v_mfma_f32_16x16x32_bf16 v[78:81], v[150:153], v[200:203], v[78:81]
	v_mfma_f32_16x16x32_bf16 v[74:77], v[160:163], v[200:203], v[74:77]
	v_mfma_f32_16x16x32_bf16 v[126:129], v[154:157], v[180:183], v[126:129]
	v_mfma_f32_16x16x32_bf16 v[122:125], v[172:175], v[180:183], v[122:125]
	v_mfma_f32_16x16x32_bf16 v[110:113], v[154:157], v[188:191], v[110:113]
	v_mfma_f32_16x16x32_bf16 v[106:109], v[172:175], v[188:191], v[106:109]
	v_mfma_f32_16x16x32_bf16 v[94:97], v[154:157], v[196:199], v[94:97]
	v_mfma_f32_16x16x32_bf16 v[90:93], v[172:175], v[196:199], v[90:93]
	v_mfma_f32_16x16x32_bf16 v[78:81], v[154:157], v[204:207], v[78:81]
	v_mfma_f32_16x16x32_bf16 v[74:77], v[172:175], v[204:207], v[74:77]
	s_barrier
	s_add_i32 s43, 0, 0x14000
	s_add_i32 s42, s42, s3
	v_add_u32_e32 v171, s43, v166
	v_lshl_add_u64 v[224:225], s[4:5], 0, v[132:133]
	s_mov_b32 m0, s42
	ds_read_b128 v[208:211], v171
	ds_read_b128 v[212:215], v171 offset:1024
	ds_read_b128 v[216:219], v171 offset:2048
	ds_read_b128 v[238:241], v171 offset:3072
	global_load_lds_dwordx4 v[224:225], off
	v_lshl_add_u64 v[230:231], s[4:5], 0, v[136:137]
	s_add_i32 m0, s42, 0x2000
	s_nop 0
	global_load_lds_dwordx4 v[230:231], off
	s_barrier
	s_waitcnt lgkmcnt(0)
	s_waitcnt lgkmcnt(0)
	v_mfma_f32_16x16x32_bf16 v[118:121], v[208:211], v[176:179], v[118:121]
	v_mfma_f32_16x16x32_bf16 v[114:117], v[216:219], v[176:179], v[114:117]
	v_mfma_f32_16x16x32_bf16 v[102:105], v[208:211], v[184:187], v[102:105]
	v_mfma_f32_16x16x32_bf16 v[98:101], v[216:219], v[184:187], v[98:101]
	v_mfma_f32_16x16x32_bf16 v[86:89], v[208:211], v[192:195], v[86:89]
	v_mfma_f32_16x16x32_bf16 v[82:85], v[216:219], v[192:195], v[82:85]
	v_mfma_f32_16x16x32_bf16 v[70:73], v[208:211], v[200:203], v[70:73]
	v_mfma_f32_16x16x32_bf16 v[66:69], v[216:219], v[200:203], v[66:69]
	v_mfma_f32_16x16x32_bf16 v[118:121], v[212:215], v[180:183], v[118:121]
	v_mfma_f32_16x16x32_bf16 v[114:117], v[238:241], v[180:183], v[114:117]
	v_mfma_f32_16x16x32_bf16 v[102:105], v[212:215], v[188:191], v[102:105]
	v_mfma_f32_16x16x32_bf16 v[98:101], v[238:241], v[188:191], v[98:101]
	v_mfma_f32_16x16x32_bf16 v[86:89], v[212:215], v[196:199], v[86:89]
	v_mfma_f32_16x16x32_bf16 v[82:85], v[238:241], v[196:199], v[82:85]
	v_mfma_f32_16x16x32_bf16 v[70:73], v[212:215], v[204:207], v[70:73]
	v_mfma_f32_16x16x32_bf16 v[66:69], v[238:241], v[204:207], v[66:69]
	s_mov_b32 m0, s8
	v_lshl_add_u64 v[232:233], v[164:165], 0, v[130:131]
	s_barrier
	ds_read_b128 v[176:179], v169 offset:16384
	ds_read_b128 v[180:183], v169 offset:17408
	ds_read_b128 v[184:187], v169 offset:18432
	ds_read_b128 v[188:191], v169 offset:19456
	ds_read_b128 v[192:195], v169 offset:20480
	ds_read_b128 v[196:199], v169 offset:21504
	ds_read_b128 v[200:203], v169 offset:22528
	ds_read_b128 v[204:207], v169 offset:23552
	global_load_lds_dwordx4 v[232:233], off
	v_lshl_add_u64 v[242:243], v[164:165], 0, v[134:135]
	s_mov_b32 m0, s9
	s_nop 0
	global_load_lds_dwordx4 v[242:243], off
	s_barrier
	s_waitcnt lgkmcnt(0)
	s_waitcnt lgkmcnt(0)
	v_mfma_f32_16x16x32_bf16 v[54:57], v[150:153], v[176:179], v[54:57]
	v_mfma_f32_16x16x32_bf16 v[50:53], v[160:163], v[176:179], v[50:53]
	v_mfma_f32_16x16x32_bf16 v[38:41], v[150:153], v[184:187], v[38:41]
	v_mfma_f32_16x16x32_bf16 v[34:37], v[160:163], v[184:187], v[34:37]
	v_mfma_f32_16x16x32_bf16 v[22:25], v[150:153], v[192:195], v[22:25]
	v_mfma_f32_16x16x32_bf16 v[18:21], v[160:163], v[192:195], v[18:21]
	v_mfma_f32_16x16x32_bf16 v[6:9], v[150:153], v[200:203], v[6:9]
	v_mfma_f32_16x16x32_bf16 v[2:5], v[160:163], v[200:203], v[2:5]
	v_mfma_f32_16x16x32_bf16 v[54:57], v[154:157], v[180:183], v[54:57]
	v_mfma_f32_16x16x32_bf16 v[50:53], v[172:175], v[180:183], v[50:53]
	v_mfma_f32_16x16x32_bf16 v[38:41], v[154:157], v[188:191], v[38:41]
	v_mfma_f32_16x16x32_bf16 v[34:37], v[172:175], v[188:191], v[34:37]
	v_mfma_f32_16x16x32_bf16 v[22:25], v[154:157], v[196:199], v[22:25]
	v_mfma_f32_16x16x32_bf16 v[18:21], v[172:175], v[196:199], v[18:21]
	v_mfma_f32_16x16x32_bf16 v[6:9], v[154:157], v[204:207], v[6:9]
	v_mfma_f32_16x16x32_bf16 v[2:5], v[172:175], v[204:207], v[2:5]
	s_barrier
	s_add_u32 s4, s4, s94
	s_addc_u32 s5, s5, 0
	s_add_i32 s42, s43, s3
	v_lshl_add_u64 v[244:245], s[4:5], 0, v[132:133]
	s_mov_b32 m0, s42
	v_lshl_add_u64 v[246:247], s[4:5], 0, v[136:137]
	global_load_lds_dwordx4 v[244:245], off
	s_add_i32 m0, s42, 0x2000
	s_nop 0
	global_load_lds_dwordx4 v[246:247], off
	s_waitcnt vmcnt(6)
	s_barrier
	v_mfma_f32_16x16x32_bf16 v[62:65], v[208:211], v[176:179], v[62:65]
	v_mfma_f32_16x16x32_bf16 v[58:61], v[216:219], v[176:179], v[58:61]
	v_mfma_f32_16x16x32_bf16 v[46:49], v[208:211], v[184:187], v[46:49]
	v_mfma_f32_16x16x32_bf16 v[42:45], v[216:219], v[184:187], v[42:45]
	v_mfma_f32_16x16x32_bf16 v[30:33], v[208:211], v[192:195], v[30:33]
	v_mfma_f32_16x16x32_bf16 v[26:29], v[216:219], v[192:195], v[26:29]
	v_mfma_f32_16x16x32_bf16 v[14:17], v[208:211], v[200:203], v[14:17]
	v_mfma_f32_16x16x32_bf16 v[10:13], v[216:219], v[200:203], v[10:13]
	v_mfma_f32_16x16x32_bf16 v[62:65], v[212:215], v[180:183], v[62:65]
	v_mfma_f32_16x16x32_bf16 v[58:61], v[238:241], v[180:183], v[58:61]
	v_mfma_f32_16x16x32_bf16 v[46:49], v[212:215], v[188:191], v[46:49]
	v_mfma_f32_16x16x32_bf16 v[42:45], v[238:241], v[188:191], v[42:45]
	v_mfma_f32_16x16x32_bf16 v[30:33], v[212:215], v[196:199], v[30:33]
	v_mfma_f32_16x16x32_bf16 v[26:29], v[238:241], v[196:199], v[26:29]
	v_mfma_f32_16x16x32_bf16 v[14:17], v[212:215], v[204:207], v[14:17]
	v_mfma_f32_16x16x32_bf16 v[10:13], v[238:241], v[204:207], v[10:13]
	s_add_i32 s4, 0, 0x18000
	v_add_u32_e32 v171, s4, v166
	s_barrier
	ds_read_b128 v[150:153], v171
	ds_read_b128 v[154:157], v171 offset:1024
	ds_read_b128 v[160:163], v171 offset:2048
	ds_read_b128 v[172:175], v171 offset:3072
	v_lshl_add_u64 v[164:165], v[164:165], 0, s[94:95]
	s_mov_b32 m0, s10
	v_lshl_add_u64 v[208:209], v[164:165], 0, v[130:131]
	ds_read_b128 v[176:179], v169 offset:32768
	ds_read_b128 v[180:183], v169 offset:33792
	ds_read_b128 v[184:187], v169 offset:34816
	ds_read_b128 v[188:191], v169 offset:35840
	ds_read_b128 v[192:195], v169 offset:36864
	ds_read_b128 v[196:199], v169 offset:37888
	ds_read_b128 v[200:203], v169 offset:38912
	ds_read_b128 v[204:207], v169 offset:39936
	global_load_lds_dwordx4 v[208:209], off
	v_lshl_add_u64 v[164:165], v[164:165], 0, v[134:135]
	s_mov_b32 m0, s11
	s_nop 0
	global_load_lds_dwordx4 v[164:165], off
	s_waitcnt lgkmcnt(8)
	s_barrier
	s_waitcnt lgkmcnt(0)
	s_waitcnt lgkmcnt(0)
	v_mfma_f32_16x16x32_bf16 v[126:129], v[150:153], v[176:179], v[126:129]
	v_mfma_f32_16x16x32_bf16 v[122:125], v[160:163], v[176:179], v[122:125]
	v_mfma_f32_16x16x32_bf16 v[110:113], v[150:153], v[184:187], v[110:113]
	v_mfma_f32_16x16x32_bf16 v[106:109], v[160:163], v[184:187], v[106:109]
	v_mfma_f32_16x16x32_bf16 v[94:97], v[150:153], v[192:195], v[94:97]
	v_mfma_f32_16x16x32_bf16 v[90:93], v[160:163], v[192:195], v[90:93]
	v_mfma_f32_16x16x32_bf16 v[78:81], v[150:153], v[200:203], v[78:81]
	v_mfma_f32_16x16x32_bf16 v[74:77], v[160:163], v[200:203], v[74:77]
	v_mfma_f32_16x16x32_bf16 v[126:129], v[154:157], v[180:183], v[126:129]
	v_mfma_f32_16x16x32_bf16 v[122:125], v[172:175], v[180:183], v[122:125]
	v_mfma_f32_16x16x32_bf16 v[110:113], v[154:157], v[188:191], v[110:113]
	v_mfma_f32_16x16x32_bf16 v[106:109], v[172:175], v[188:191], v[106:109]
	v_mfma_f32_16x16x32_bf16 v[94:97], v[154:157], v[196:199], v[94:97]
	v_mfma_f32_16x16x32_bf16 v[90:93], v[172:175], v[196:199], v[90:93]
	v_mfma_f32_16x16x32_bf16 v[78:81], v[154:157], v[204:207], v[78:81]
	v_mfma_f32_16x16x32_bf16 v[74:77], v[172:175], v[204:207], v[74:77]
	s_barrier
	s_add_i32 s5, 0, 0x1c000
	v_add_u32_e32 v164, s5, v166
	s_add_i32 s4, s4, s3
	ds_read_b128 v[208:211], v164
	ds_read_b128 v[212:215], v164 offset:1024
	ds_read_b128 v[216:219], v164 offset:2048
	ds_read_b128 v[238:241], v164 offset:3072
	v_lshl_add_u64 v[164:165], v[224:225], 0, s[84:85]
	s_mov_b32 m0, s4
	s_nop 0
	global_load_lds_dwordx4 v[164:165], off
	v_lshl_add_u64 v[164:165], v[230:231], 0, s[84:85]
	s_add_i32 m0, s4, 0x2000
	s_nop 0
	global_load_lds_dwordx4 v[164:165], off
	s_barrier
	s_waitcnt lgkmcnt(0)
	s_waitcnt lgkmcnt(0)
	v_mfma_f32_16x16x32_bf16 v[118:121], v[208:211], v[176:179], v[118:121]
	v_mfma_f32_16x16x32_bf16 v[114:117], v[216:219], v[176:179], v[114:117]
	v_mfma_f32_16x16x32_bf16 v[102:105], v[208:211], v[184:187], v[102:105]
	v_mfma_f32_16x16x32_bf16 v[98:101], v[216:219], v[184:187], v[98:101]
	v_mfma_f32_16x16x32_bf16 v[86:89], v[208:211], v[192:195], v[86:89]
	v_mfma_f32_16x16x32_bf16 v[82:85], v[216:219], v[192:195], v[82:85]
	v_mfma_f32_16x16x32_bf16 v[70:73], v[208:211], v[200:203], v[70:73]
	v_mfma_f32_16x16x32_bf16 v[66:69], v[216:219], v[200:203], v[66:69]
	v_mfma_f32_16x16x32_bf16 v[118:121], v[212:215], v[180:183], v[118:121]
	v_mfma_f32_16x16x32_bf16 v[114:117], v[238:241], v[180:183], v[114:117]
	v_mfma_f32_16x16x32_bf16 v[102:105], v[212:215], v[188:191], v[102:105]
	v_mfma_f32_16x16x32_bf16 v[98:101], v[238:241], v[188:191], v[98:101]
	v_mfma_f32_16x16x32_bf16 v[86:89], v[212:215], v[196:199], v[86:89]
	v_mfma_f32_16x16x32_bf16 v[82:85], v[238:241], v[196:199], v[82:85]
	v_mfma_f32_16x16x32_bf16 v[70:73], v[212:215], v[204:207], v[70:73]
	v_mfma_f32_16x16x32_bf16 v[66:69], v[238:241], v[204:207], v[66:69]
	s_mov_b32 m0, s12
	v_lshl_add_u64 v[164:165], v[232:233], 0, s[84:85]
	s_barrier
	ds_read_b128 v[176:179], v169 offset:49152
	ds_read_b128 v[180:183], v169 offset:50176
	ds_read_b128 v[184:187], v169 offset:51200
	ds_read_b128 v[188:191], v169 offset:52224
	ds_read_b128 v[192:195], v169 offset:53248
	ds_read_b128 v[196:199], v169 offset:54272
	ds_read_b128 v[200:203], v169 offset:55296
	ds_read_b128 v[204:207], v169 offset:56320
	global_load_lds_dwordx4 v[164:165], off
	v_lshl_add_u64 v[164:165], v[242:243], 0, s[84:85]
	s_mov_b32 m0, s22
	s_nop 0
	global_load_lds_dwordx4 v[164:165], off
	s_barrier
	s_waitcnt lgkmcnt(0)
	s_waitcnt lgkmcnt(0)
	v_mfma_f32_16x16x32_bf16 v[54:57], v[150:153], v[176:179], v[54:57]
	v_mfma_f32_16x16x32_bf16 v[50:53], v[160:163], v[176:179], v[50:53]
	v_mfma_f32_16x16x32_bf16 v[38:41], v[150:153], v[184:187], v[38:41]
	v_mfma_f32_16x16x32_bf16 v[34:37], v[160:163], v[184:187], v[34:37]
	v_mfma_f32_16x16x32_bf16 v[22:25], v[150:153], v[192:195], v[22:25]
	v_mfma_f32_16x16x32_bf16 v[18:21], v[160:163], v[192:195], v[18:21]
	v_mfma_f32_16x16x32_bf16 v[6:9], v[150:153], v[200:203], v[6:9]
	v_mfma_f32_16x16x32_bf16 v[2:5], v[160:163], v[200:203], v[2:5]
	v_mfma_f32_16x16x32_bf16 v[54:57], v[154:157], v[180:183], v[54:57]
	v_mfma_f32_16x16x32_bf16 v[50:53], v[172:175], v[180:183], v[50:53]
	v_mfma_f32_16x16x32_bf16 v[38:41], v[154:157], v[188:191], v[38:41]
	v_mfma_f32_16x16x32_bf16 v[34:37], v[172:175], v[188:191], v[34:37]
	v_mfma_f32_16x16x32_bf16 v[22:25], v[154:157], v[196:199], v[22:25]
	v_mfma_f32_16x16x32_bf16 v[18:21], v[172:175], v[196:199], v[18:21]
	v_mfma_f32_16x16x32_bf16 v[6:9], v[154:157], v[204:207], v[6:9]
	v_mfma_f32_16x16x32_bf16 v[2:5], v[172:175], v[204:207], v[2:5]
	s_barrier
	s_add_i32 s4, s5, s3
	v_lshl_add_u64 v[150:151], v[244:245], 0, s[84:85]
	s_mov_b32 m0, s4
	s_nop 0
	global_load_lds_dwordx4 v[150:151], off
	v_lshl_add_u64 v[150:151], v[246:247], 0, s[84:85]
	s_add_i32 m0, s4, 0x2000
	s_nop 0
	global_load_lds_dwordx4 v[150:151], off
	s_waitcnt vmcnt(6)
	s_barrier
	v_mfma_f32_16x16x32_bf16 v[62:65], v[208:211], v[176:179], v[62:65]
	v_mfma_f32_16x16x32_bf16 v[58:61], v[216:219], v[176:179], v[58:61]
	v_mfma_f32_16x16x32_bf16 v[46:49], v[208:211], v[184:187], v[46:49]
	v_mfma_f32_16x16x32_bf16 v[42:45], v[216:219], v[184:187], v[42:45]
	v_mfma_f32_16x16x32_bf16 v[30:33], v[208:211], v[192:195], v[30:33]
	v_mfma_f32_16x16x32_bf16 v[26:29], v[216:219], v[192:195], v[26:29]
	v_mfma_f32_16x16x32_bf16 v[14:17], v[208:211], v[200:203], v[14:17]
	v_mfma_f32_16x16x32_bf16 v[10:13], v[216:219], v[200:203], v[10:13]
	v_mfma_f32_16x16x32_bf16 v[62:65], v[212:215], v[180:183], v[62:65]
	v_mfma_f32_16x16x32_bf16 v[58:61], v[238:241], v[180:183], v[58:61]
	v_mfma_f32_16x16x32_bf16 v[46:49], v[212:215], v[188:191], v[46:49]
	v_mfma_f32_16x16x32_bf16 v[42:45], v[238:241], v[188:191], v[42:45]
	v_mfma_f32_16x16x32_bf16 v[30:33], v[212:215], v[196:199], v[30:33]
	v_mfma_f32_16x16x32_bf16 v[26:29], v[238:241], v[196:199], v[26:29]
	v_mfma_f32_16x16x32_bf16 v[14:17], v[212:215], v[204:207], v[14:17]
	v_mfma_f32_16x16x32_bf16 v[10:13], v[238:241], v[204:207], v[10:13]
	s_add_u32 s6, s6, 0x100
	s_addc_u32 s7, s7, 0
	v_lshl_add_u64 v[148:149], v[148:149], 0, s[86:87]
	s_cmp_ge_u32 s17, s13
	s_mov_b32 s4, s17
	s_barrier
	s_cbranch_scc0 .LBB0_461
	v_cmp_lt_i32_e32 vcc, v227, v222
	ds_read2st64_b32 v[148:149], v170 offset1:1
	ds_read2st64_b32 v[150:151], v170 offset0:2 offset1:3
	ds_read2st64_b32 v[156:157], v170 offset0:4 offset1:5
	ds_read2st64_b32 v[160:161], v170 offset0:6 offset1:7
	v_cndmask_b32_e32 v152, v221, v227, vcc
	v_lshlrev_b32_e32 v171, 2, v152
	s_waitcnt lgkmcnt(0)
	ds_bpermute_b32 v153, v171, v148
	ds_bpermute_b32 v152, v171, v149
	v_cmp_lt_i32_e32 vcc, v228, v222
	v_mov_b32_e32 v155, v148
	s_mov_b32 s4, 0x3a800000
	v_cndmask_b32_e32 v154, v221, v228, vcc
	v_lshlrev_b32_e32 v172, 2, v154
	v_mov_b32_e32 v154, v149
	s_waitcnt lgkmcnt(0)
	v_pk_add_f32 v[148:149], v[154:155], v[152:153]
	ds_bpermute_b32 v153, v172, v149
	ds_bpermute_b32 v152, v172, v148
	ds_bpermute_b32 v174, v171, v161
	ds_bpermute_b32 v175, v171, v160
	s_waitcnt lgkmcnt(0)
	v_pk_add_f32 v[148:149], v[148:149], v[152:153]
	s_nop 0
	v_pk_fma_f32 v[162:163], v[148:149], s[4:5], v[158:159] op_sel_hi:[1,0,0]
	ds_bpermute_b32 v149, v171, v150
	v_mul_f32_e32 v148, 0x4b800000, v163
	v_cmp_gt_f32_e32 vcc, s88, v163
	s_nop 1
	v_cndmask_b32_e32 v148, v163, v148, vcc
	v_rsq_f32_e32 v152, v148
	ds_bpermute_b32 v148, v171, v151
	v_mul_f32_e32 v153, 0x45800000, v152
	v_cndmask_b32_e32 v164, v152, v153, vcc
	v_mov_b32_e32 v152, v151
	v_mov_b32_e32 v153, v150
	v_pk_mul_f32 v[128:129], v[128:129], v[164:165] op_sel_hi:[1,0]
	v_pk_mul_f32 v[124:125], v[124:125], v[164:165] op_sel_hi:[1,0]
	s_waitcnt lgkmcnt(0)
	v_pk_add_f32 v[152:153], v[152:153], v[148:149]
	v_pk_mul_f32 v[126:127], v[126:127], v[164:165] op_sel_hi:[1,0]
	v_max_f32_e32 v148, v128, v129
	v_pk_mul_f32 v[122:123], v[122:123], v[164:165] op_sel_hi:[1,0]
	v_max_f32_e32 v149, v124, v125
	v_max3_f32 v148, v126, v127, v148
	v_max3_f32 v149, v122, v123, v149
	v_pk_mul_f32 v[120:121], v[120:121], v[164:165] op_sel_hi:[1,0]
	v_pk_mul_f32 v[116:117], v[116:117], v[164:165] op_sel_hi:[1,0]
	v_max3_f32 v148, v148, s89, v149
	v_pk_mul_f32 v[118:119], v[118:119], v[164:165] op_sel_hi:[1,0]
	v_max_f32_e32 v149, v120, v121
	v_pk_mul_f32 v[114:115], v[114:115], v[164:165] op_sel_hi:[1,0]
	v_max_f32_e32 v150, v116, v117
	v_max3_f32 v149, v118, v119, v149
	v_max3_f32 v150, v114, v115, v150
	v_max3_f32 v163, v148, v149, v150
	ds_bpermute_b32 v164, v171, v163
	ds_bpermute_b32 v151, v171, v156
	v_mov_b32_e32 v149, v156
	v_mov_b32_e32 v148, v157
	ds_bpermute_b32 v150, v171, v157
	s_waitcnt lgkmcnt(0)
	v_max_f32_e32 v156, v164, v164
	v_max_f32_e32 v157, v163, v156
	ds_bpermute_b32 v163, v172, v157
	v_mov_b32_e32 v156, v161
	v_pk_add_f32 v[148:149], v[148:149], v[150:151]
	ds_bpermute_b32 v155, v172, v153
	ds_bpermute_b32 v154, v172, v152
	s_waitcnt lgkmcnt(0)
	v_max_f32_e32 v163, v163, v163
	v_max_f32_e32 v164, v157, v163
	v_mov_b32_e32 v178, v164
	v_sub_f32_e32 v157, v126, v164
	v_sub_f32_e32 v163, v127, v164
	v_sub_f32_e32 v165, v128, v164
	v_sub_f32_e32 v173, v129, v164
	v_mul_f32_e32 v157, 0x3fb8aa3b, v157
	v_mul_f32_e32 v163, 0x3fb8aa3b, v163
	v_mul_f32_e32 v165, 0x3fb8aa3b, v165
	v_mul_f32_e32 v173, 0x3fb8aa3b, v173
	v_exp_f32_e32 v157, v157
	v_exp_f32_e32 v163, v163
	v_exp_f32_e32 v165, v165
	v_exp_f32_e32 v173, v173
	v_sub_f32_e32 v176, v125, v164
	v_mov_b32_e32 v126, v157
	v_mov_b32_e32 v127, v163
	v_add_f32_e32 v157, v157, v163
	v_sub_f32_e32 v163, v122, v164
	v_mov_b32_e32 v128, v165
	v_mov_b32_e32 v129, v173
	v_add_f32_e32 v161, v165, v173
	v_sub_f32_e32 v165, v123, v164
	v_sub_f32_e32 v173, v124, v164
	v_mul_f32_e32 v163, 0x3fb8aa3b, v163
	v_mul_f32_e32 v165, 0x3fb8aa3b, v165
	v_mul_f32_e32 v173, 0x3fb8aa3b, v173
	v_mul_f32_e32 v176, 0x3fb8aa3b, v176
	v_exp_f32_e32 v163, v163
	v_exp_f32_e32 v165, v165
	v_exp_f32_e32 v173, v173
	v_exp_f32_e32 v176, v176
	v_add_f32_e32 v157, v157, v161
	v_mov_b32_e32 v122, v163
	v_mov_b32_e32 v123, v165
	v_add_f32_e32 v161, v163, v165
	v_sub_f32_e32 v165, v118, v164
	v_mov_b32_e32 v124, v173
	v_mov_b32_e32 v125, v176
	v_add_f32_e32 v163, v173, v176
	v_sub_f32_e32 v173, v119, v164
	v_sub_f32_e32 v176, v120, v164
	v_sub_f32_e32 v177, v121, v164
	v_mul_f32_e32 v165, 0x3fb8aa3b, v165
	v_mul_f32_e32 v173, 0x3fb8aa3b, v173
	v_mul_f32_e32 v176, 0x3fb8aa3b, v176
	v_mul_f32_e32 v177, 0x3fb8aa3b, v177
	v_exp_f32_e32 v165, v165
	v_exp_f32_e32 v173, v173
	v_exp_f32_e32 v176, v176
	v_exp_f32_e32 v177, v177
	v_add_f32_e32 v157, 0, v157
	v_add_f32_e32 v161, v161, v163
	v_add_f32_e32 v157, v161, v157
	v_mov_b32_e32 v118, v165
	v_mov_b32_e32 v119, v173
	v_add_f32_e32 v161, v165, v173
	v_mov_b32_e32 v120, v176
	v_mov_b32_e32 v121, v177
	v_add_f32_e32 v163, v176, v177
	v_sub_f32_e32 v165, v114, v164
	v_sub_f32_e32 v173, v115, v164
	v_sub_f32_e32 v176, v116, v164
	v_sub_f32_e32 v177, v117, v164
	v_mul_f32_e32 v165, 0x3fb8aa3b, v165
	v_mul_f32_e32 v173, 0x3fb8aa3b, v173
	v_mul_f32_e32 v176, 0x3fb8aa3b, v176
	v_mul_f32_e32 v177, 0x3fb8aa3b, v177
	v_exp_f32_e32 v165, v165
	v_exp_f32_e32 v173, v173
	v_exp_f32_e32 v176, v176
	v_exp_f32_e32 v177, v177
	v_add_f32_e32 v161, v161, v163
	v_add_f32_e32 v157, v161, v157
	v_mov_b32_e32 v114, v165
	v_mov_b32_e32 v115, v173
	v_add_f32_e32 v161, v165, v173
	v_mov_b32_e32 v116, v176
	v_mov_b32_e32 v117, v177
	v_add_f32_e32 v163, v176, v177
	v_add_f32_e32 v161, v161, v163
	v_add_f32_e32 v163, v161, v157
	ds_bpermute_b32 v165, v171, v163
	v_mov_b32_e32 v157, v160
	v_pk_add_f32 v[156:157], v[156:157], v[174:175]
	ds_bpermute_b32 v151, v172, v149
	ds_bpermute_b32 v150, v172, v148
	s_waitcnt lgkmcnt(0)
	v_add_f32_e32 v163, v163, v165
	ds_bpermute_b32 v161, v172, v157
	ds_bpermute_b32 v160, v172, v156
	ds_bpermute_b32 v165, v172, v163
	v_cmp_gt_f32_e32 vcc, s88, v162
	v_add_u32_e32 v173, s45, v168
	s_and_saveexec_b64 s[4:5], s[38:39]
	s_cbranch_execz .LBB0_464
	s_waitcnt lgkmcnt(0)
	v_add_f32_e32 v165, v163, v165
	ds_write_b64 v173, v[164:165]
.LBB0_464:
	s_or_b64 exec, exec, s[4:5]
	v_mul_f32_e32 v163, 0x4b800000, v162
	v_cndmask_b32_e32 v162, v162, v163, vcc
	v_rsq_f32_e32 v162, v162
	s_nop 0
	v_mul_f32_e32 v163, 0x45800000, v162
	v_cndmask_b32_e32 v162, v162, v163, vcc
	v_pk_mul_f32 v[112:113], v[112:113], v[162:163] op_sel_hi:[1,0]
	v_pk_mul_f32 v[110:111], v[110:111], v[162:163] op_sel_hi:[1,0]
	v_max_f32_e32 v163, v112, v113
	v_max3_f32 v163, v110, v111, v163
	v_pk_mul_f32 v[108:109], v[108:109], v[162:163] op_sel_hi:[1,0]
	v_pk_mul_f32 v[106:107], v[106:107], v[162:163] op_sel_hi:[1,0]
	v_max_f32_e32 v164, v108, v109
	v_max3_f32 v164, v106, v107, v164
	v_max3_f32 v163, v163, s89, v164
	v_pk_mul_f32 v[104:105], v[104:105], v[162:163] op_sel_hi:[1,0]
	v_pk_mul_f32 v[100:101], v[100:101], v[162:163] op_sel_hi:[1,0]
	v_pk_mul_f32 v[102:103], v[102:103], v[162:163] op_sel_hi:[1,0]
	v_max_f32_e32 v164, v104, v105
	v_pk_mul_f32 v[98:99], v[98:99], v[162:163] op_sel_hi:[1,0]
	v_max_f32_e32 v162, v100, v101
	v_max3_f32 v164, v102, v103, v164
	v_max3_f32 v162, v98, v99, v162
	v_max3_f32 v162, v163, v164, v162
	ds_bpermute_b32 v163, v171, v162
	s_waitcnt lgkmcnt(0)
	v_max_f32_e32 v163, v163, v163
	v_max_f32_e32 v162, v162, v163
	ds_bpermute_b32 v163, v172, v162
	s_waitcnt lgkmcnt(0)
	v_max_f32_e32 v163, v163, v163
	v_max_f32_e32 v162, v162, v163
	v_mov_b32_e32 v179, v162
	v_sub_f32_e32 v163, v110, v162
	v_sub_f32_e32 v164, v111, v162
	v_mul_f32_e32 v163, 0x3fb8aa3b, v163
	v_mul_f32_e32 v164, 0x3fb8aa3b, v164
	v_exp_f32_e32 v163, v163
	v_exp_f32_e32 v164, v164
	v_sub_f32_e32 v165, v113, v162
	v_mul_f32_e32 v165, 0x3fb8aa3b, v165
	v_exp_f32_e32 v165, v165
	v_mov_b32_e32 v110, v163
	v_mov_b32_e32 v111, v164
	v_add_f32_e32 v163, v163, v164
	v_sub_f32_e32 v164, v112, v162
	v_mul_f32_e32 v164, 0x3fb8aa3b, v164
	v_exp_f32_e32 v164, v164
	v_sub_f32_e32 v174, v109, v162
	v_mul_f32_e32 v174, 0x3fb8aa3b, v174
	v_exp_f32_e32 v174, v174
	v_mov_b32_e32 v113, v165
	v_mov_b32_e32 v112, v164
	v_add_f32_e32 v164, v164, v165
	v_add_f32_e32 v163, v163, v164
	v_sub_f32_e32 v164, v106, v162
	v_sub_f32_e32 v165, v107, v162
	v_mul_f32_e32 v164, 0x3fb8aa3b, v164
	v_mul_f32_e32 v165, 0x3fb8aa3b, v165
	v_exp_f32_e32 v164, v164
	v_exp_f32_e32 v165, v165
	v_add_f32_e32 v163, 0, v163
	v_mov_b32_e32 v106, v164
	v_mov_b32_e32 v107, v165
	v_add_f32_e32 v164, v164, v165
	v_sub_f32_e32 v165, v108, v162
	v_mul_f32_e32 v165, 0x3fb8aa3b, v165
	v_exp_f32_e32 v165, v165
	s_nop 0
	v_mov_b32_e32 v109, v174
	v_mov_b32_e32 v108, v165
	v_add_f32_e32 v165, v165, v174
	v_add_f32_e32 v164, v164, v165
	v_add_f32_e32 v163, v164, v163
	v_sub_f32_e32 v164, v102, v162
	v_sub_f32_e32 v165, v103, v162
	v_mul_f32_e32 v164, 0x3fb8aa3b, v164
	v_mul_f32_e32 v165, 0x3fb8aa3b, v165
	v_exp_f32_e32 v164, v164
	v_exp_f32_e32 v165, v165
	v_sub_f32_e32 v174, v105, v162
	v_mul_f32_e32 v174, 0x3fb8aa3b, v174
	v_exp_f32_e32 v174, v174
	v_mov_b32_e32 v102, v164
	v_mov_b32_e32 v103, v165
	v_add_f32_e32 v164, v164, v165
	v_sub_f32_e32 v165, v104, v162
	v_mul_f32_e32 v165, 0x3fb8aa3b, v165
	v_exp_f32_e32 v165, v165
	s_nop 0
	v_mov_b32_e32 v105, v174
	v_mov_b32_e32 v104, v165
	v_add_f32_e32 v165, v165, v174
	v_add_f32_e32 v164, v164, v165
	v_add_f32_e32 v163, v164, v163
	v_sub_f32_e32 v164, v98, v162
	v_sub_f32_e32 v165, v99, v162
	v_mul_f32_e32 v164, 0x3fb8aa3b, v164
	v_mul_f32_e32 v165, 0x3fb8aa3b, v165
	v_exp_f32_e32 v164, v164
	v_exp_f32_e32 v165, v165
	v_sub_f32_e32 v174, v101, v162
	v_mul_f32_e32 v174, 0x3fb8aa3b, v174
	v_exp_f32_e32 v174, v174
	v_mov_b32_e32 v98, v164
	v_mov_b32_e32 v99, v165
	v_add_f32_e32 v164, v164, v165
	v_sub_f32_e32 v165, v100, v162
	v_mul_f32_e32 v165, 0x3fb8aa3b, v165
	v_exp_f32_e32 v165, v165
	s_nop 0
	v_mov_b32_e32 v101, v174
	v_mov_b32_e32 v100, v165
	v_add_f32_e32 v165, v165, v174
	v_add_f32_e32 v164, v164, v165
	v_add_f32_e32 v163, v164, v163
	ds_bpermute_b32 v164, v171, v163
	s_waitcnt lgkmcnt(0)
	v_add_f32_e32 v163, v163, v164
	ds_bpermute_b32 v164, v172, v163
	s_and_saveexec_b64 s[4:5], s[38:39]
	s_cbranch_execz .LBB0_466
	s_waitcnt lgkmcnt(0)
	v_add_f32_e32 v163, v163, v164
	ds_write_b64 v173, v[162:163] offset:512
.LBB0_466:
	s_or_b64 exec, exec, s[4:5]
	v_pk_add_f32 v[152:153], v[152:153], v[154:155]
	s_mov_b32 s4, 0x3a800000
	v_pk_fma_f32 v[152:153], v[152:153], s[4:5], v[158:159] op_sel_hi:[1,0,0]
	s_nop 0
	v_mul_f32_e32 v154, 0x4b800000, v153
	v_cmp_gt_f32_e32 vcc, s88, v153
	s_nop 1
	v_cndmask_b32_e32 v153, v153, v154, vcc
	v_rsq_f32_e32 v153, v153
	s_nop 0
	v_mul_f32_e32 v154, 0x45800000, v153
	v_cndmask_b32_e32 v154, v153, v154, vcc
	v_pk_mul_f32 v[92:93], v[92:93], v[154:155] op_sel_hi:[1,0]
	v_pk_mul_f32 v[96:97], v[96:97], v[154:155] op_sel_hi:[1,0]
	v_pk_mul_f32 v[94:95], v[94:95], v[154:155] op_sel_hi:[1,0]
	v_pk_mul_f32 v[90:91], v[90:91], v[154:155] op_sel_hi:[1,0]
	v_max_f32_e32 v155, v92, v93
	v_max_f32_e32 v153, v96, v97
	v_max3_f32 v155, v90, v91, v155
	v_max3_f32 v153, v94, v95, v153
	v_pk_mul_f32 v[88:89], v[88:89], v[154:155] op_sel_hi:[1,0]
	v_max3_f32 v153, v153, s89, v155
	v_pk_mul_f32 v[86:87], v[86:87], v[154:155] op_sel_hi:[1,0]
	v_max_f32_e32 v155, v88, v89
	v_max3_f32 v155, v86, v87, v155
	v_pk_mul_f32 v[84:85], v[84:85], v[154:155] op_sel_hi:[1,0]
	v_pk_mul_f32 v[82:83], v[82:83], v[154:155] op_sel_hi:[1,0]
	v_max_f32_e32 v154, v84, v85
	v_max3_f32 v154, v82, v83, v154
	v_max3_f32 v153, v153, v155, v154
	ds_bpermute_b32 v154, v171, v153
	v_cmp_gt_f32_e32 vcc, s88, v152
	s_waitcnt lgkmcnt(0)
	v_max_f32_e32 v154, v154, v154
	v_max_f32_e32 v153, v153, v154
	ds_bpermute_b32 v154, v172, v153
	s_waitcnt lgkmcnt(0)
	v_max_f32_e32 v154, v154, v154
	v_max_f32_e32 v154, v153, v154
	v_mov_b32_e32 v180, v154
	v_sub_f32_e32 v153, v94, v154
	v_sub_f32_e32 v155, v95, v154
	v_sub_f32_e32 v162, v96, v154
	v_sub_f32_e32 v163, v97, v154
	v_mul_f32_e32 v153, 0x3fb8aa3b, v153
	v_mul_f32_e32 v155, 0x3fb8aa3b, v155
	v_mul_f32_e32 v162, 0x3fb8aa3b, v162
	v_mul_f32_e32 v163, 0x3fb8aa3b, v163
	v_exp_f32_e32 v153, v153
	v_exp_f32_e32 v155, v155
	v_exp_f32_e32 v162, v162
	v_exp_f32_e32 v163, v163
	v_sub_f32_e32 v164, v92, v154
	v_mov_b32_e32 v94, v153
	v_mov_b32_e32 v95, v155
	v_add_f32_e32 v153, v153, v155
	v_sub_f32_e32 v165, v93, v154
	v_mov_b32_e32 v96, v162
	v_mov_b32_e32 v97, v163
	v_add_f32_e32 v155, v162, v163
	v_sub_f32_e32 v162, v90, v154
	v_sub_f32_e32 v163, v91, v154
	v_mul_f32_e32 v162, 0x3fb8aa3b, v162
	v_mul_f32_e32 v163, 0x3fb8aa3b, v163
	v_mul_f32_e32 v164, 0x3fb8aa3b, v164
	v_mul_f32_e32 v165, 0x3fb8aa3b, v165
	v_exp_f32_e32 v162, v162
	v_exp_f32_e32 v163, v163
	v_exp_f32_e32 v164, v164
	v_exp_f32_e32 v165, v165
	v_add_f32_e32 v153, v153, v155
	v_mov_b32_e32 v90, v162
	v_mov_b32_e32 v91, v163
	v_add_f32_e32 v155, v162, v163
	v_sub_f32_e32 v163, v86, v154
	v_mov_b32_e32 v92, v164
	v_mov_b32_e32 v93, v165
	v_add_f32_e32 v162, v164, v165
	v_sub_f32_e32 v164, v87, v154
	v_sub_f32_e32 v165, v88, v154
	v_sub_f32_e32 v174, v89, v154
	v_mul_f32_e32 v163, 0x3fb8aa3b, v163
	v_mul_f32_e32 v164, 0x3fb8aa3b, v164
	v_mul_f32_e32 v165, 0x3fb8aa3b, v165
	v_mul_f32_e32 v174, 0x3fb8aa3b, v174
	v_exp_f32_e32 v163, v163
	v_exp_f32_e32 v164, v164
	v_exp_f32_e32 v165, v165
	v_exp_f32_e32 v174, v174
	v_add_f32_e32 v153, 0, v153
	v_add_f32_e32 v155, v155, v162
	v_add_f32_e32 v153, v155, v153
	v_mov_b32_e32 v86, v163
	v_mov_b32_e32 v87, v164
	v_add_f32_e32 v155, v163, v164
	v_mov_b32_e32 v88, v165
	v_mov_b32_e32 v89, v174
	v_add_f32_e32 v162, v165, v174
	v_sub_f32_e32 v163, v82, v154
	v_sub_f32_e32 v164, v83, v154
	v_sub_f32_e32 v165, v84, v154
	v_sub_f32_e32 v174, v85, v154
	v_mul_f32_e32 v163, 0x3fb8aa3b, v163
	v_mul_f32_e32 v164, 0x3fb8aa3b, v164
	v_mul_f32_e32 v165, 0x3fb8aa3b, v165
	v_mul_f32_e32 v174, 0x3fb8aa3b, v174
	v_exp_f32_e32 v163, v163
	v_exp_f32_e32 v164, v164
	v_exp_f32_e32 v165, v165
	v_exp_f32_e32 v174, v174
	v_add_f32_e32 v155, v155, v162
	v_add_f32_e32 v153, v155, v153
	v_mov_b32_e32 v82, v163
	v_mov_b32_e32 v83, v164
	v_add_f32_e32 v155, v163, v164
	v_mov_b32_e32 v84, v165
	v_mov_b32_e32 v85, v174
	v_add_f32_e32 v162, v165, v174
	v_add_f32_e32 v155, v155, v162
	v_add_f32_e32 v153, v155, v153
	ds_bpermute_b32 v155, v171, v153
	s_waitcnt lgkmcnt(0)
	v_add_f32_e32 v153, v153, v155
	ds_bpermute_b32 v155, v172, v153
	s_and_saveexec_b64 s[4:5], s[38:39]
	s_cbranch_execz .LBB0_468
	s_waitcnt lgkmcnt(0)
	v_add_f32_e32 v155, v153, v155
	ds_write_b64 v173, v[154:155] offset:1024
.LBB0_468:
	s_or_b64 exec, exec, s[4:5]
	v_mul_f32_e32 v153, 0x4b800000, v152
	v_cndmask_b32_e32 v152, v152, v153, vcc
	v_rsq_f32_e32 v152, v152
	s_nop 0
	v_mul_f32_e32 v153, 0x45800000, v152
	v_cndmask_b32_e32 v152, v152, v153, vcc
	v_pk_mul_f32 v[80:81], v[80:81], v[152:153] op_sel_hi:[1,0]
	v_pk_mul_f32 v[78:79], v[78:79], v[152:153] op_sel_hi:[1,0]
	v_max_f32_e32 v153, v80, v81
	v_max3_f32 v153, v78, v79, v153
	v_pk_mul_f32 v[76:77], v[76:77], v[152:153] op_sel_hi:[1,0]
	v_pk_mul_f32 v[74:75], v[74:75], v[152:153] op_sel_hi:[1,0]
	v_max_f32_e32 v154, v76, v77
	v_max3_f32 v154, v74, v75, v154
	v_max3_f32 v153, v153, s89, v154
	v_pk_mul_f32 v[72:73], v[72:73], v[152:153] op_sel_hi:[1,0]
	v_pk_mul_f32 v[68:69], v[68:69], v[152:153] op_sel_hi:[1,0]
	v_pk_mul_f32 v[70:71], v[70:71], v[152:153] op_sel_hi:[1,0]
	v_max_f32_e32 v154, v72, v73
	v_pk_mul_f32 v[66:67], v[66:67], v[152:153] op_sel_hi:[1,0]
	v_max_f32_e32 v152, v68, v69
	v_max3_f32 v154, v70, v71, v154
	v_max3_f32 v152, v66, v67, v152
	v_max3_f32 v152, v153, v154, v152
	ds_bpermute_b32 v153, v171, v152
	s_waitcnt lgkmcnt(0)
	v_max_f32_e32 v153, v153, v153
	v_max_f32_e32 v152, v152, v153
	ds_bpermute_b32 v153, v172, v152
	s_waitcnt lgkmcnt(0)
	v_max_f32_e32 v153, v153, v153
	v_max_f32_e32 v152, v152, v153
	v_mov_b32_e32 v181, v152
	v_sub_f32_e32 v153, v78, v152
	v_sub_f32_e32 v154, v79, v152
	v_mul_f32_e32 v153, 0x3fb8aa3b, v153
	v_mul_f32_e32 v154, 0x3fb8aa3b, v154
	v_exp_f32_e32 v153, v153
	v_exp_f32_e32 v154, v154
	v_sub_f32_e32 v155, v81, v152
	v_mul_f32_e32 v155, 0x3fb8aa3b, v155
	v_exp_f32_e32 v155, v155
	v_mov_b32_e32 v78, v153
	v_mov_b32_e32 v79, v154
	v_add_f32_e32 v153, v153, v154
	v_sub_f32_e32 v154, v80, v152
	v_mul_f32_e32 v154, 0x3fb8aa3b, v154
	v_exp_f32_e32 v154, v154
	v_sub_f32_e32 v162, v77, v152
	v_mul_f32_e32 v162, 0x3fb8aa3b, v162
	v_exp_f32_e32 v162, v162
	v_mov_b32_e32 v81, v155
	v_mov_b32_e32 v80, v154
	v_add_f32_e32 v154, v154, v155
	v_add_f32_e32 v153, v153, v154
	v_sub_f32_e32 v154, v74, v152
	v_sub_f32_e32 v155, v75, v152
	v_mul_f32_e32 v154, 0x3fb8aa3b, v154
	v_mul_f32_e32 v155, 0x3fb8aa3b, v155
	v_exp_f32_e32 v154, v154
	v_exp_f32_e32 v155, v155
	v_add_f32_e32 v153, 0, v153
	v_mov_b32_e32 v74, v154
	v_mov_b32_e32 v75, v155
	v_add_f32_e32 v154, v154, v155
	v_sub_f32_e32 v155, v76, v152
	v_mul_f32_e32 v155, 0x3fb8aa3b, v155
	v_exp_f32_e32 v155, v155
	s_nop 0
	v_mov_b32_e32 v77, v162
	v_mov_b32_e32 v76, v155
	v_add_f32_e32 v155, v155, v162
	v_add_f32_e32 v154, v154, v155
	v_add_f32_e32 v153, v154, v153
	v_sub_f32_e32 v154, v70, v152
	v_sub_f32_e32 v155, v71, v152
	v_mul_f32_e32 v154, 0x3fb8aa3b, v154
	v_mul_f32_e32 v155, 0x3fb8aa3b, v155
	v_exp_f32_e32 v154, v154
	v_exp_f32_e32 v155, v155
	v_sub_f32_e32 v162, v73, v152
	v_mul_f32_e32 v162, 0x3fb8aa3b, v162
	v_exp_f32_e32 v162, v162
	v_mov_b32_e32 v70, v154
	v_mov_b32_e32 v71, v155
	v_add_f32_e32 v154, v154, v155
	v_sub_f32_e32 v155, v72, v152
	v_mul_f32_e32 v155, 0x3fb8aa3b, v155
	v_exp_f32_e32 v155, v155
	s_nop 0
	v_mov_b32_e32 v73, v162
	v_mov_b32_e32 v72, v155
	v_add_f32_e32 v155, v155, v162
	v_add_f32_e32 v154, v154, v155
	v_add_f32_e32 v153, v154, v153
	v_sub_f32_e32 v154, v66, v152
	v_sub_f32_e32 v155, v67, v152
	v_mul_f32_e32 v154, 0x3fb8aa3b, v154
	v_mul_f32_e32 v155, 0x3fb8aa3b, v155
	v_exp_f32_e32 v154, v154
	v_exp_f32_e32 v155, v155
	v_sub_f32_e32 v162, v69, v152
	v_mul_f32_e32 v162, 0x3fb8aa3b, v162
	v_exp_f32_e32 v162, v162
	v_mov_b32_e32 v66, v154
	v_mov_b32_e32 v67, v155
	v_add_f32_e32 v154, v154, v155
	v_sub_f32_e32 v155, v68, v152
	v_mul_f32_e32 v155, 0x3fb8aa3b, v155
	v_exp_f32_e32 v155, v155
	s_nop 0
	v_mov_b32_e32 v69, v162
	v_mov_b32_e32 v68, v155
	v_add_f32_e32 v155, v155, v162
	v_add_f32_e32 v154, v154, v155
	v_add_f32_e32 v153, v154, v153
	ds_bpermute_b32 v154, v171, v153
	s_waitcnt lgkmcnt(0)
	v_add_f32_e32 v153, v153, v154
	ds_bpermute_b32 v154, v172, v153
	s_and_saveexec_b64 s[4:5], s[38:39]
	s_cbranch_execz .LBB0_470
	s_waitcnt lgkmcnt(0)
	v_add_f32_e32 v153, v153, v154
	ds_write_b64 v173, v[152:153] offset:1536
.LBB0_470:
	s_or_b64 exec, exec, s[4:5]
	v_pk_add_f32 v[148:149], v[148:149], v[150:151]
	s_mov_b32 s4, 0x3a800000
	v_pk_fma_f32 v[162:163], v[148:149], s[4:5], v[158:159] op_sel_hi:[1,0,0]
	s_nop 0
	v_mul_f32_e32 v148, 0x4b800000, v163
	v_cmp_gt_f32_e32 vcc, s88, v163
	s_nop 1
	v_cndmask_b32_e32 v148, v163, v148, vcc
	v_rsq_f32_e32 v148, v148
	s_nop 0
	v_mul_f32_e32 v149, 0x45800000, v148
	v_cndmask_b32_e32 v164, v148, v149, vcc
	v_pk_mul_f32 v[152:153], v[56:57], v[164:165] op_sel_hi:[1,0]
	v_pk_mul_f32 v[148:149], v[52:53], v[164:165] op_sel_hi:[1,0]
	s_waitcnt lgkmcnt(0)
	v_pk_mul_f32 v[154:155], v[54:55], v[164:165] op_sel_hi:[1,0]
	v_max_f32_e32 v52, v152, v153
	v_pk_mul_f32 v[150:151], v[50:51], v[164:165] op_sel_hi:[1,0]
	v_max_f32_e32 v50, v148, v149
	v_max3_f32 v52, v154, v155, v52
	v_max3_f32 v50, v150, v151, v50
	v_pk_mul_f32 v[54:55], v[64:65], v[164:165] op_sel_hi:[1,0]
	v_max3_f32 v56, v52, s89, v50
	v_pk_mul_f32 v[62:63], v[62:63], v[164:165] op_sel_hi:[1,0]
	v_max_f32_e32 v50, v54, v55
	v_max3_f32 v57, v62, v63, v50
	v_pk_mul_f32 v[50:51], v[60:61], v[164:165] op_sel_hi:[1,0]
	v_pk_mul_f32 v[52:53], v[58:59], v[164:165] op_sel_hi:[1,0]
	v_max_f32_e32 v58, v50, v51
	v_max3_f32 v58, v52, v53, v58
	v_max3_f32 v56, v56, v57, v58
	ds_bpermute_b32 v57, v171, v56
	v_cmp_gt_f32_e32 vcc, s88, v162
	s_waitcnt lgkmcnt(0)
	v_max_f32_e32 v57, v57, v57
	v_max_f32_e32 v56, v56, v57
	ds_bpermute_b32 v57, v172, v56
	s_waitcnt lgkmcnt(0)
	v_max_f32_e32 v57, v57, v57
	v_max_f32_e32 v56, v56, v57
	v_mov_b32_e32 v182, v56
	v_sub_f32_e32 v57, v154, v56
	v_sub_f32_e32 v58, v155, v56
	v_sub_f32_e32 v59, v152, v56
	v_sub_f32_e32 v60, v153, v56
	v_mul_f32_e32 v57, 0x3fb8aa3b, v57
	v_mul_f32_e32 v58, 0x3fb8aa3b, v58
	v_mul_f32_e32 v59, 0x3fb8aa3b, v59
	v_mul_f32_e32 v60, 0x3fb8aa3b, v60
	v_exp_f32_e32 v57, v57
	v_exp_f32_e32 v58, v58
	v_exp_f32_e32 v59, v59
	v_exp_f32_e32 v60, v60
	v_sub_f32_e32 v61, v148, v56
	v_mov_b32_e32 v154, v57
	v_mov_b32_e32 v155, v58
	v_add_f32_e32 v57, v57, v58
	v_sub_f32_e32 v64, v149, v56
	v_mov_b32_e32 v152, v59
	v_mov_b32_e32 v153, v60
	v_add_f32_e32 v58, v59, v60
	v_sub_f32_e32 v59, v150, v56
	v_sub_f32_e32 v60, v151, v56
	v_mul_f32_e32 v59, 0x3fb8aa3b, v59
	v_mul_f32_e32 v60, 0x3fb8aa3b, v60
	v_mul_f32_e32 v61, 0x3fb8aa3b, v61
	v_mul_f32_e32 v64, 0x3fb8aa3b, v64
	v_exp_f32_e32 v59, v59
	v_exp_f32_e32 v60, v60
	v_exp_f32_e32 v61, v61
	v_exp_f32_e32 v64, v64
	v_add_f32_e32 v57, v57, v58
	v_mov_b32_e32 v150, v59
	v_mov_b32_e32 v151, v60
	v_add_f32_e32 v58, v59, v60
	v_sub_f32_e32 v60, v62, v56
	v_mov_b32_e32 v148, v61
	v_mov_b32_e32 v149, v64
	v_add_f32_e32 v59, v61, v64
	v_sub_f32_e32 v61, v63, v56
	v_sub_f32_e32 v64, v54, v56
	v_sub_f32_e32 v65, v55, v56
	v_mul_f32_e32 v60, 0x3fb8aa3b, v60
	v_mul_f32_e32 v61, 0x3fb8aa3b, v61
	v_mul_f32_e32 v64, 0x3fb8aa3b, v64
	v_mul_f32_e32 v65, 0x3fb8aa3b, v65
	v_exp_f32_e32 v60, v60
	v_exp_f32_e32 v61, v61
	v_exp_f32_e32 v64, v64
	v_exp_f32_e32 v65, v65
	v_add_f32_e32 v57, 0, v57
	v_add_f32_e32 v58, v58, v59
	v_add_f32_e32 v57, v58, v57
	v_mov_b32_e32 v62, v60
	v_mov_b32_e32 v63, v61
	v_add_f32_e32 v58, v60, v61
	v_mov_b32_e32 v54, v64
	v_mov_b32_e32 v55, v65
	v_add_f32_e32 v59, v64, v65
	v_sub_f32_e32 v60, v52, v56
	v_sub_f32_e32 v61, v53, v56
	v_sub_f32_e32 v64, v50, v56
	v_sub_f32_e32 v65, v51, v56
	v_mul_f32_e32 v60, 0x3fb8aa3b, v60
	v_mul_f32_e32 v61, 0x3fb8aa3b, v61
	v_mul_f32_e32 v64, 0x3fb8aa3b, v64
	v_mul_f32_e32 v65, 0x3fb8aa3b, v65
	v_exp_f32_e32 v60, v60
	v_exp_f32_e32 v61, v61
	v_exp_f32_e32 v64, v64
	v_exp_f32_e32 v65, v65
	v_add_f32_e32 v58, v58, v59
	v_add_f32_e32 v57, v58, v57
	v_mov_b32_e32 v52, v60
	v_mov_b32_e32 v53, v61
	v_add_f32_e32 v58, v60, v61
	v_mov_b32_e32 v50, v64
	v_mov_b32_e32 v51, v65
	v_add_f32_e32 v59, v64, v65
	v_add_f32_e32 v58, v58, v59
	v_add_f32_e32 v57, v58, v57
	ds_bpermute_b32 v58, v171, v57
	s_waitcnt lgkmcnt(0)
	v_add_f32_e32 v57, v57, v58
	ds_bpermute_b32 v58, v172, v57
	s_and_saveexec_b64 s[4:5], s[38:39]
	s_cbranch_execz .LBB0_472
	s_waitcnt lgkmcnt(0)
	v_add_f32_e32 v57, v57, v58
	ds_write_b64 v173, v[56:57] offset:4096
.LBB0_472:
	s_or_b64 exec, exec, s[4:5]
	v_mul_f32_e32 v56, 0x4b800000, v162
	v_cndmask_b32_e32 v56, v162, v56, vcc
	v_rsq_f32_e32 v56, v56
	s_nop 0
	v_mul_f32_e32 v57, 0x45800000, v56
	v_cndmask_b32_e32 v162, v56, v57, vcc
	s_waitcnt lgkmcnt(0)
	v_pk_mul_f32 v[58:59], v[40:41], v[162:163] op_sel_hi:[1,0]
	v_pk_mul_f32 v[56:57], v[36:37], v[162:163] op_sel_hi:[1,0]
	v_pk_mul_f32 v[64:65], v[38:39], v[162:163] op_sel_hi:[1,0]
	v_max_f32_e32 v38, v58, v59
	v_pk_mul_f32 v[60:61], v[34:35], v[162:163] op_sel_hi:[1,0]
	v_max_f32_e32 v34, v56, v57
	v_max3_f32 v38, v64, v65, v38
	v_max3_f32 v34, v60, v61, v34
	v_max3_f32 v163, v38, s89, v34
	v_pk_mul_f32 v[38:39], v[48:49], v[162:163] op_sel_hi:[1,0]
	v_pk_mul_f32 v[40:41], v[46:47], v[162:163] op_sel_hi:[1,0]
	v_max_f32_e32 v34, v38, v39
	v_max3_f32 v46, v40, v41, v34
	v_pk_mul_f32 v[34:35], v[44:45], v[162:163] op_sel_hi:[1,0]
	v_pk_mul_f32 v[36:37], v[42:43], v[162:163] op_sel_hi:[1,0]
	v_max_f32_e32 v42, v34, v35
	v_max3_f32 v42, v36, v37, v42
	v_max3_f32 v42, v163, v46, v42
	ds_bpermute_b32 v43, v171, v42
	s_waitcnt lgkmcnt(0)
	v_max_f32_e32 v43, v43, v43
	v_max_f32_e32 v42, v42, v43
	ds_bpermute_b32 v43, v172, v42
	s_waitcnt lgkmcnt(0)
	v_max_f32_e32 v43, v43, v43
	v_max_f32_e32 v42, v42, v43
	v_mov_b32_e32 v183, v42
	v_sub_f32_e32 v43, v64, v42
	v_sub_f32_e32 v44, v65, v42
	v_mul_f32_e32 v43, 0x3fb8aa3b, v43
	v_mul_f32_e32 v44, 0x3fb8aa3b, v44
	v_exp_f32_e32 v43, v43
	v_exp_f32_e32 v44, v44
	v_sub_f32_e32 v45, v59, v42
	v_mul_f32_e32 v45, 0x3fb8aa3b, v45
	v_exp_f32_e32 v45, v45
	v_mov_b32_e32 v64, v43
	v_mov_b32_e32 v65, v44
	v_add_f32_e32 v43, v43, v44
	v_sub_f32_e32 v44, v58, v42
	v_mul_f32_e32 v44, 0x3fb8aa3b, v44
	v_exp_f32_e32 v44, v44
	v_sub_f32_e32 v46, v57, v42
	v_mul_f32_e32 v46, 0x3fb8aa3b, v46
	v_exp_f32_e32 v46, v46
	v_mov_b32_e32 v59, v45
	v_mov_b32_e32 v58, v44
	v_add_f32_e32 v44, v44, v45
	v_add_f32_e32 v43, v43, v44
	v_sub_f32_e32 v44, v60, v42
	v_sub_f32_e32 v45, v61, v42
	v_mul_f32_e32 v44, 0x3fb8aa3b, v44
	v_mul_f32_e32 v45, 0x3fb8aa3b, v45
	v_exp_f32_e32 v44, v44
	v_exp_f32_e32 v45, v45
	v_add_f32_e32 v43, 0, v43
	v_mov_b32_e32 v60, v44
	v_mov_b32_e32 v61, v45
	v_add_f32_e32 v44, v44, v45
	v_sub_f32_e32 v45, v56, v42
	v_mul_f32_e32 v45, 0x3fb8aa3b, v45
	v_exp_f32_e32 v45, v45
	s_nop 0
	v_mov_b32_e32 v57, v46
	v_mov_b32_e32 v56, v45
	v_add_f32_e32 v45, v45, v46
	v_add_f32_e32 v44, v44, v45
	v_add_f32_e32 v43, v44, v43
	v_sub_f32_e32 v44, v40, v42
	v_sub_f32_e32 v45, v41, v42
	v_mul_f32_e32 v44, 0x3fb8aa3b, v44
	v_mul_f32_e32 v45, 0x3fb8aa3b, v45
	v_exp_f32_e32 v44, v44
	v_exp_f32_e32 v45, v45
	v_sub_f32_e32 v46, v39, v42
	v_mul_f32_e32 v46, 0x3fb8aa3b, v46
	v_exp_f32_e32 v46, v46
	v_mov_b32_e32 v40, v44
	v_mov_b32_e32 v41, v45
	v_add_f32_e32 v44, v44, v45
	v_sub_f32_e32 v45, v38, v42
	v_mul_f32_e32 v45, 0x3fb8aa3b, v45
	v_exp_f32_e32 v45, v45
	s_nop 0
	v_mov_b32_e32 v39, v46
	v_mov_b32_e32 v38, v45
	v_add_f32_e32 v45, v45, v46
	v_add_f32_e32 v44, v44, v45
	v_add_f32_e32 v43, v44, v43
	v_sub_f32_e32 v44, v36, v42
	v_sub_f32_e32 v45, v37, v42
	v_mul_f32_e32 v44, 0x3fb8aa3b, v44
	v_mul_f32_e32 v45, 0x3fb8aa3b, v45
	v_exp_f32_e32 v44, v44
	v_exp_f32_e32 v45, v45
	v_sub_f32_e32 v46, v35, v42
	v_mul_f32_e32 v46, 0x3fb8aa3b, v46
	v_exp_f32_e32 v46, v46
	v_mov_b32_e32 v36, v44
	v_mov_b32_e32 v37, v45
	v_add_f32_e32 v44, v44, v45
	v_sub_f32_e32 v45, v34, v42
	v_mul_f32_e32 v45, 0x3fb8aa3b, v45
	v_exp_f32_e32 v45, v45
	s_nop 0
	v_mov_b32_e32 v35, v46
	v_mov_b32_e32 v34, v45
	v_add_f32_e32 v45, v45, v46
	v_add_f32_e32 v44, v44, v45
	v_add_f32_e32 v43, v44, v43
	ds_bpermute_b32 v44, v171, v43
	s_waitcnt lgkmcnt(0)
	v_add_f32_e32 v43, v43, v44
	ds_bpermute_b32 v44, v172, v43
	s_and_saveexec_b64 s[4:5], s[38:39]
	s_cbranch_execz .LBB0_474
	s_waitcnt lgkmcnt(0)
	v_add_f32_e32 v43, v43, v44
	ds_write_b64 v173, v[42:43] offset:4608
.LBB0_474:
	s_or_b64 exec, exec, s[4:5]
	v_pk_add_f32 v[42:43], v[156:157], v[160:161]
	s_mov_b32 s4, 0x3a800000
	v_pk_fma_f32 v[156:157], v[42:43], s[4:5], v[158:159] op_sel_hi:[1,0,0]
	s_nop 0
	v_mul_f32_e32 v42, 0x4b800000, v157
	v_cmp_gt_f32_e32 vcc, s88, v157
	s_nop 1
	v_cndmask_b32_e32 v42, v157, v42, vcc
	v_rsq_f32_e32 v42, v42
	s_nop 0
	v_mul_f32_e32 v43, 0x45800000, v42
	v_cndmask_b32_e32 v160, v42, v43, vcc
	v_pk_mul_f32 v[46:47], v[24:25], v[160:161] op_sel_hi:[1,0]
	v_pk_mul_f32 v[42:43], v[20:21], v[160:161] op_sel_hi:[1,0]
	v_pk_mul_f32 v[48:49], v[22:23], v[160:161] op_sel_hi:[1,0]
	v_max_f32_e32 v20, v46, v47
	s_waitcnt lgkmcnt(0)
	v_pk_mul_f32 v[44:45], v[18:19], v[160:161] op_sel_hi:[1,0]
	v_max_f32_e32 v18, v42, v43
	v_max3_f32 v20, v48, v49, v20
	v_max3_f32 v18, v44, v45, v18
	v_pk_mul_f32 v[22:23], v[32:33], v[160:161] op_sel_hi:[1,0]
	v_max3_f32 v24, v20, s89, v18
	v_pk_mul_f32 v[30:31], v[30:31], v[160:161] op_sel_hi:[1,0]
	v_max_f32_e32 v18, v22, v23
	v_max3_f32 v25, v30, v31, v18
	v_pk_mul_f32 v[18:19], v[28:29], v[160:161] op_sel_hi:[1,0]
	v_pk_mul_f32 v[20:21], v[26:27], v[160:161] op_sel_hi:[1,0]
	v_max_f32_e32 v26, v18, v19
	v_max3_f32 v26, v20, v21, v26
	v_max3_f32 v24, v24, v25, v26
	ds_bpermute_b32 v25, v171, v24
	v_cmp_gt_f32_e32 vcc, s88, v156
	s_waitcnt lgkmcnt(0)
	v_max_f32_e32 v25, v25, v25
	v_max_f32_e32 v24, v24, v25
	ds_bpermute_b32 v25, v172, v24
	s_waitcnt lgkmcnt(0)
	v_max_f32_e32 v25, v25, v25
	v_max_f32_e32 v24, v24, v25
	v_mov_b32_e32 v184, v24
	v_sub_f32_e32 v25, v48, v24
	v_sub_f32_e32 v26, v49, v24
	v_sub_f32_e32 v27, v46, v24
	v_sub_f32_e32 v28, v47, v24
	v_mul_f32_e32 v25, 0x3fb8aa3b, v25
	v_mul_f32_e32 v26, 0x3fb8aa3b, v26
	v_mul_f32_e32 v27, 0x3fb8aa3b, v27
	v_mul_f32_e32 v28, 0x3fb8aa3b, v28
	v_exp_f32_e32 v25, v25
	v_exp_f32_e32 v26, v26
	v_exp_f32_e32 v27, v27
	v_exp_f32_e32 v28, v28
	v_sub_f32_e32 v29, v42, v24
	v_mov_b32_e32 v48, v25
	v_mov_b32_e32 v49, v26
	v_add_f32_e32 v25, v25, v26
	v_sub_f32_e32 v32, v43, v24
	v_mov_b32_e32 v46, v27
	v_mov_b32_e32 v47, v28
	v_add_f32_e32 v26, v27, v28
	v_sub_f32_e32 v27, v44, v24
	v_sub_f32_e32 v28, v45, v24
	v_mul_f32_e32 v27, 0x3fb8aa3b, v27
	v_mul_f32_e32 v28, 0x3fb8aa3b, v28
	v_mul_f32_e32 v29, 0x3fb8aa3b, v29
	v_mul_f32_e32 v32, 0x3fb8aa3b, v32
	v_exp_f32_e32 v27, v27
	v_exp_f32_e32 v28, v28
	v_exp_f32_e32 v29, v29
	v_exp_f32_e32 v32, v32
	v_add_f32_e32 v25, v25, v26
	v_mov_b32_e32 v44, v27
	v_mov_b32_e32 v45, v28
	v_add_f32_e32 v26, v27, v28
	v_sub_f32_e32 v28, v30, v24
	v_mov_b32_e32 v42, v29
	v_mov_b32_e32 v43, v32
	v_add_f32_e32 v27, v29, v32
	v_sub_f32_e32 v29, v31, v24
	v_sub_f32_e32 v32, v22, v24
	v_sub_f32_e32 v33, v23, v24
	v_mul_f32_e32 v28, 0x3fb8aa3b, v28
	v_mul_f32_e32 v29, 0x3fb8aa3b, v29
	v_mul_f32_e32 v32, 0x3fb8aa3b, v32
	v_mul_f32_e32 v33, 0x3fb8aa3b, v33
	v_exp_f32_e32 v28, v28
	v_exp_f32_e32 v29, v29
	v_exp_f32_e32 v32, v32
	v_exp_f32_e32 v33, v33
	v_add_f32_e32 v25, 0, v25
	v_add_f32_e32 v26, v26, v27
	v_add_f32_e32 v25, v26, v25
	v_mov_b32_e32 v30, v28
	v_mov_b32_e32 v31, v29
	v_add_f32_e32 v26, v28, v29
	v_mov_b32_e32 v22, v32
	v_mov_b32_e32 v23, v33
	v_add_f32_e32 v27, v32, v33
	v_sub_f32_e32 v28, v20, v24
	v_sub_f32_e32 v29, v21, v24
	v_sub_f32_e32 v32, v18, v24
	v_sub_f32_e32 v33, v19, v24
	v_mul_f32_e32 v28, 0x3fb8aa3b, v28
	v_mul_f32_e32 v29, 0x3fb8aa3b, v29
	v_mul_f32_e32 v32, 0x3fb8aa3b, v32
	v_mul_f32_e32 v33, 0x3fb8aa3b, v33
	v_exp_f32_e32 v28, v28
	v_exp_f32_e32 v29, v29
	v_exp_f32_e32 v32, v32
	v_exp_f32_e32 v33, v33
	v_add_f32_e32 v26, v26, v27
	v_add_f32_e32 v25, v26, v25
	v_mov_b32_e32 v20, v28
	v_mov_b32_e32 v21, v29
	v_add_f32_e32 v26, v28, v29
	v_mov_b32_e32 v18, v32
	v_mov_b32_e32 v19, v33
	v_add_f32_e32 v27, v32, v33
	v_add_f32_e32 v26, v26, v27
	v_add_f32_e32 v25, v26, v25
	ds_bpermute_b32 v26, v171, v25
	s_waitcnt lgkmcnt(0)
	v_add_f32_e32 v25, v25, v26
	ds_bpermute_b32 v26, v172, v25
	s_and_saveexec_b64 s[4:5], s[38:39]
	s_cbranch_execz .LBB0_476
	s_waitcnt lgkmcnt(0)
	v_add_f32_e32 v25, v25, v26
	ds_write_b64 v173, v[24:25] offset:5120
.LBB0_476:
	s_or_b64 exec, exec, s[4:5]
	v_mul_f32_e32 v24, 0x4b800000, v156
	v_cndmask_b32_e32 v24, v156, v24, vcc
	v_rsq_f32_e32 v24, v24
	s_nop 0
	v_mul_f32_e32 v25, 0x45800000, v24
	v_cndmask_b32_e32 v156, v24, v25, vcc
	s_waitcnt lgkmcnt(0)
	v_pk_mul_f32 v[26:27], v[8:9], v[156:157] op_sel_hi:[1,0]
	v_pk_mul_f32 v[24:25], v[4:5], v[156:157] op_sel_hi:[1,0]
	v_pk_mul_f32 v[32:33], v[6:7], v[156:157] op_sel_hi:[1,0]
	v_max_f32_e32 v6, v26, v27
	v_pk_mul_f32 v[28:29], v[2:3], v[156:157] op_sel_hi:[1,0]
	v_max_f32_e32 v2, v24, v25
	v_max3_f32 v6, v32, v33, v6
	v_max3_f32 v2, v28, v29, v2
	v_max3_f32 v157, v6, s89, v2
	v_pk_mul_f32 v[6:7], v[16:17], v[156:157] op_sel_hi:[1,0]
	v_pk_mul_f32 v[8:9], v[14:15], v[156:157] op_sel_hi:[1,0]
	v_max_f32_e32 v2, v6, v7
	v_max3_f32 v14, v8, v9, v2
	v_pk_mul_f32 v[2:3], v[12:13], v[156:157] op_sel_hi:[1,0]
	v_pk_mul_f32 v[4:5], v[10:11], v[156:157] op_sel_hi:[1,0]
	v_max_f32_e32 v10, v2, v3
	v_max3_f32 v10, v4, v5, v10
	v_max3_f32 v10, v157, v14, v10
	ds_bpermute_b32 v11, v171, v10
	s_waitcnt lgkmcnt(0)
	v_max_f32_e32 v11, v11, v11
	v_max_f32_e32 v10, v10, v11
	ds_bpermute_b32 v11, v172, v10
	s_waitcnt lgkmcnt(0)
	v_max_f32_e32 v11, v11, v11
	v_max_f32_e32 v10, v10, v11
	v_mov_b32_e32 v185, v10
	v_sub_f32_e32 v11, v32, v10
	v_sub_f32_e32 v12, v33, v10
	v_mul_f32_e32 v11, 0x3fb8aa3b, v11
	v_mul_f32_e32 v12, 0x3fb8aa3b, v12
	v_exp_f32_e32 v11, v11
	v_exp_f32_e32 v12, v12
	v_sub_f32_e32 v13, v27, v10
	v_mul_f32_e32 v13, 0x3fb8aa3b, v13
	v_exp_f32_e32 v13, v13
	v_mov_b32_e32 v32, v11
	v_mov_b32_e32 v33, v12
	v_add_f32_e32 v11, v11, v12
	v_sub_f32_e32 v12, v26, v10
	v_mul_f32_e32 v12, 0x3fb8aa3b, v12
	v_exp_f32_e32 v12, v12
	v_sub_f32_e32 v14, v25, v10
	v_mul_f32_e32 v14, 0x3fb8aa3b, v14
	v_exp_f32_e32 v14, v14
	v_mov_b32_e32 v27, v13
	v_mov_b32_e32 v26, v12
	v_add_f32_e32 v12, v12, v13
	v_add_f32_e32 v11, v11, v12
	v_sub_f32_e32 v12, v28, v10
	v_sub_f32_e32 v13, v29, v10
	v_mul_f32_e32 v12, 0x3fb8aa3b, v12
	v_mul_f32_e32 v13, 0x3fb8aa3b, v13
	v_exp_f32_e32 v12, v12
	v_exp_f32_e32 v13, v13
	v_add_f32_e32 v11, 0, v11
	v_mov_b32_e32 v28, v12
	v_mov_b32_e32 v29, v13
	v_add_f32_e32 v12, v12, v13
	v_sub_f32_e32 v13, v24, v10
	v_mul_f32_e32 v13, 0x3fb8aa3b, v13
	v_exp_f32_e32 v13, v13
	s_nop 0
	v_mov_b32_e32 v25, v14
	v_mov_b32_e32 v24, v13
	v_add_f32_e32 v13, v13, v14
	v_add_f32_e32 v12, v12, v13
	v_add_f32_e32 v11, v12, v11
	v_sub_f32_e32 v12, v8, v10
	v_sub_f32_e32 v13, v9, v10
	v_mul_f32_e32 v12, 0x3fb8aa3b, v12
	v_mul_f32_e32 v13, 0x3fb8aa3b, v13
	v_exp_f32_e32 v12, v12
	v_exp_f32_e32 v13, v13
	v_sub_f32_e32 v14, v7, v10
	v_mul_f32_e32 v14, 0x3fb8aa3b, v14
	v_exp_f32_e32 v14, v14
	v_mov_b32_e32 v8, v12
	v_mov_b32_e32 v9, v13
	v_add_f32_e32 v12, v12, v13
	v_sub_f32_e32 v13, v6, v10
	v_mul_f32_e32 v13, 0x3fb8aa3b, v13
	v_exp_f32_e32 v13, v13
	s_nop 0
	v_mov_b32_e32 v7, v14
	v_mov_b32_e32 v6, v13
	v_add_f32_e32 v13, v13, v14
	v_add_f32_e32 v12, v12, v13
	v_add_f32_e32 v11, v12, v11
	v_sub_f32_e32 v12, v4, v10
	v_sub_f32_e32 v13, v5, v10
	v_mul_f32_e32 v12, 0x3fb8aa3b, v12
	v_mul_f32_e32 v13, 0x3fb8aa3b, v13
	v_exp_f32_e32 v12, v12
	v_exp_f32_e32 v13, v13
	v_sub_f32_e32 v14, v3, v10
	v_mul_f32_e32 v14, 0x3fb8aa3b, v14
	v_exp_f32_e32 v14, v14
	v_mov_b32_e32 v4, v12
	v_mov_b32_e32 v5, v13
	v_add_f32_e32 v12, v12, v13
	v_sub_f32_e32 v13, v2, v10
	v_mul_f32_e32 v13, 0x3fb8aa3b, v13
	v_exp_f32_e32 v13, v13
	s_nop 0
	v_mov_b32_e32 v3, v14
	v_mov_b32_e32 v2, v13
	v_add_f32_e32 v13, v13, v14
	v_add_f32_e32 v12, v12, v13
	v_add_f32_e32 v11, v12, v11
	ds_bpermute_b32 v12, v171, v11
	s_waitcnt lgkmcnt(0)
	v_add_f32_e32 v11, v11, v12
	ds_bpermute_b32 v12, v172, v11
	s_and_saveexec_b64 s[4:5], s[38:39]
	s_cbranch_execz .LBB0_453
	s_waitcnt lgkmcnt(0)
	v_add_f32_e32 v11, v11, v12
	ds_write_b64 v173, v[10:11] offset:5632
	s_branch .LBB0_453
